# GEMM K-loops: B-fragment LDS reads of phases 1/5 moved into the read-free load slots of phases 8/4 (counted vmcnt(10) keeps the staged tile landed)
# speedup vs baseline: 1.0060x; 1.0017x over previous
.LBB0_261:
	s_ashr_i32 s41, s40, 31
	v_cmp_lt_i64_e32 vcc, s[8:9], v[162:163]
	s_lshl_b64 s[8:9], s[40:41], 20
	s_add_u32 s92, s96, s8
	s_addc_u32 s93, s97, s9
	s_and_b64 s[8:9], vcc, exec
	s_cselect_b32 s10, s93, s5
	s_cselect_b32 s11, s92, s4
	s_ashr_i32 s39, s38, 31
	s_lshl_b64 s[8:9], s[38:39], 20
	v_readlane_b32 s34, v252, 58
	v_readlane_b32 s35, v252, 59
	s_add_u32 s94, s34, s8
	s_addc_u32 s95, s35, s9
	s_and_b64 s[8:9], vcc, exec
	s_cselect_b32 s20, s95, s7
	s_cselect_b32 s34, s94, s6
	s_add_u32 s4, s4, 0x80080
	s_addc_u32 s5, s5, 0
	s_add_u32 s35, s6, 0x100
	v_mov_b32_e32 v0, 0
	s_addc_u32 s36, s7, 0
	s_mov_b32 s37, -2
	v_mov_b32_e32 v1, v0
	v_mov_b32_e32 v2, v0
	v_mov_b32_e32 v3, v0
	v_mov_b32_e32 v4, v0
	v_mov_b32_e32 v5, v0
	v_mov_b32_e32 v6, v0
	v_mov_b32_e32 v7, v0
	v_mov_b32_e32 v16, v0
	v_mov_b32_e32 v17, v0
	v_mov_b32_e32 v18, v0
	v_mov_b32_e32 v19, v0
	v_mov_b32_e32 v20, v0
	v_mov_b32_e32 v21, v0
	v_mov_b32_e32 v22, v0
	v_mov_b32_e32 v23, v0
	v_mov_b32_e32 v32, v0
	v_mov_b32_e32 v33, v0
	v_mov_b32_e32 v34, v0
	v_mov_b32_e32 v35, v0
	v_mov_b32_e32 v36, v0
	v_mov_b32_e32 v37, v0
	v_mov_b32_e32 v38, v0
	v_mov_b32_e32 v39, v0
	v_mov_b32_e32 v48, v0
	v_mov_b32_e32 v49, v0
	v_mov_b32_e32 v50, v0
	v_mov_b32_e32 v51, v0
	v_mov_b32_e32 v52, v0
	v_mov_b32_e32 v53, v0
	v_mov_b32_e32 v54, v0
	v_mov_b32_e32 v55, v0
	v_mov_b32_e32 v8, v0
	v_mov_b32_e32 v9, v0
	v_mov_b32_e32 v10, v0
	v_mov_b32_e32 v11, v0
	v_mov_b32_e32 v12, v0
	v_mov_b32_e32 v13, v0
	v_mov_b32_e32 v14, v0
	v_mov_b32_e32 v15, v0
	v_mov_b32_e32 v24, v0
	v_mov_b32_e32 v25, v0
	v_mov_b32_e32 v26, v0
	v_mov_b32_e32 v27, v0
	v_mov_b32_e32 v28, v0
	v_mov_b32_e32 v29, v0
	v_mov_b32_e32 v30, v0
	v_mov_b32_e32 v31, v0
	v_mov_b32_e32 v40, v0
	v_mov_b32_e32 v41, v0
	v_mov_b32_e32 v42, v0
	v_mov_b32_e32 v43, v0
	v_mov_b32_e32 v44, v0
	v_mov_b32_e32 v45, v0
	v_mov_b32_e32 v46, v0
	v_mov_b32_e32 v47, v0
	v_mov_b32_e32 v56, v0
	v_mov_b32_e32 v57, v0
	v_mov_b32_e32 v58, v0
	v_mov_b32_e32 v59, v0
	v_mov_b32_e32 v60, v0
	v_mov_b32_e32 v61, v0
	v_mov_b32_e32 v62, v0
	v_mov_b32_e32 v63, v0
	v_mov_b32_e32 v64, v0
	v_mov_b32_e32 v65, v0
	v_mov_b32_e32 v66, v0
	v_mov_b32_e32 v67, v0
	v_mov_b32_e32 v68, v0
	v_mov_b32_e32 v69, v0
	v_mov_b32_e32 v70, v0
	v_mov_b32_e32 v71, v0
	v_mov_b32_e32 v80, v0
	v_mov_b32_e32 v81, v0
	v_mov_b32_e32 v82, v0
	v_mov_b32_e32 v83, v0
	v_mov_b32_e32 v84, v0
	v_mov_b32_e32 v85, v0
	v_mov_b32_e32 v86, v0
	v_mov_b32_e32 v87, v0
	v_mov_b32_e32 v96, v0
	v_mov_b32_e32 v97, v0
	v_mov_b32_e32 v98, v0
	v_mov_b32_e32 v99, v0
	v_mov_b32_e32 v100, v0
	v_mov_b32_e32 v101, v0
	v_mov_b32_e32 v102, v0
	v_mov_b32_e32 v103, v0
	v_mov_b32_e32 v112, v0
	v_mov_b32_e32 v113, v0
	v_mov_b32_e32 v114, v0
	v_mov_b32_e32 v115, v0
	v_mov_b32_e32 v116, v0
	v_mov_b32_e32 v117, v0
	v_mov_b32_e32 v118, v0
	v_mov_b32_e32 v119, v0
	v_mov_b32_e32 v72, v0
	v_mov_b32_e32 v73, v0
	v_mov_b32_e32 v74, v0
	v_mov_b32_e32 v75, v0
	v_mov_b32_e32 v76, v0
	v_mov_b32_e32 v77, v0
	v_mov_b32_e32 v78, v0
	v_mov_b32_e32 v79, v0
	v_mov_b32_e32 v88, v0
	v_mov_b32_e32 v89, v0
	v_mov_b32_e32 v90, v0
	v_mov_b32_e32 v91, v0
	v_mov_b32_e32 v92, v0
	v_mov_b32_e32 v93, v0
	v_mov_b32_e32 v94, v0
	v_mov_b32_e32 v95, v0
	v_mov_b32_e32 v104, v0
	v_mov_b32_e32 v105, v0
	v_mov_b32_e32 v106, v0
	v_mov_b32_e32 v107, v0
	v_mov_b32_e32 v108, v0
	v_mov_b32_e32 v109, v0
	v_mov_b32_e32 v110, v0
	v_mov_b32_e32 v111, v0
	v_mov_b32_e32 v120, v0
	v_mov_b32_e32 v121, v0
	v_mov_b32_e32 v122, v0
	v_mov_b32_e32 v123, v0
	v_mov_b32_e32 v124, v0
	v_mov_b32_e32 v125, v0
	v_mov_b32_e32 v126, v0
	v_mov_b32_e32 v127, v0
	ds_read_b128 v[128:131], v181
	ds_read_b128 v[132:135], v181 offset:1024
	ds_read_b128 v[136:139], v181 offset:2048
	ds_read_b128 v[140:143], v181 offset:3072
.LBB0_262:
	s_add_u32 s6, s4, 0xfff80080
	s_addc_u32 s7, s5, -1
	s_cmp_eq_u32 s37, 28
	s_cselect_b32 s9, s10, s7
	s_cselect_b32 s8, s11, s6
	s_cselect_b32 s7, s20, s36
	s_cselect_b32 s6, s34, s35
	v_lshl_add_u64 v[176:177], s[4:5], 0, v[158:159]
	s_add_i32 m0, s44, 0xc000
	ds_read_b128 v[144:147], v182
	ds_read_b128 v[168:171], v182 offset:1024
	ds_read_b128 v[172:175], v182 offset:2048
	ds_read_b128 v[184:187], v182 offset:3072
	ds_read_b128 v[188:191], v182 offset:4096
	ds_read_b128 v[192:195], v182 offset:5120
	ds_read_b128 v[196:199], v182 offset:6144
	ds_read_b128 v[200:203], v182 offset:7168
	global_load_lds_dwordx4 v[176:177], off
	v_lshl_add_u64 v[176:177], s[4:5], 0, v[160:161]
	s_add_i32 m0, s44, 0xe000
	s_nop 0
	global_load_lds_dwordx4 v[176:177], off
	s_waitcnt lgkmcnt(8)
	s_barrier
	s_waitcnt lgkmcnt(0)
	s_setprio 1
	s_waitcnt lgkmcnt(0)
	v_mfma_f32_16x16x32_bf16 v[124:127], v[128:131], v[144:147], v[124:127]
	v_mfma_f32_16x16x32_bf16 v[120:123], v[136:139], v[144:147], v[120:123]
	v_mfma_f32_16x16x32_bf16 v[108:111], v[128:131], v[172:175], v[108:111]
	v_mfma_f32_16x16x32_bf16 v[104:107], v[136:139], v[172:175], v[104:107]
	v_mfma_f32_16x16x32_bf16 v[92:95], v[128:131], v[188:191], v[92:95]
	v_mfma_f32_16x16x32_bf16 v[88:91], v[136:139], v[188:191], v[88:91]
	v_mfma_f32_16x16x32_bf16 v[76:79], v[128:131], v[196:199], v[76:79]
	v_mfma_f32_16x16x32_bf16 v[72:75], v[136:139], v[196:199], v[72:75]
	v_mfma_f32_16x16x32_bf16 v[124:127], v[132:135], v[168:171], v[124:127]
	v_mfma_f32_16x16x32_bf16 v[120:123], v[140:143], v[168:171], v[120:123]
	v_mfma_f32_16x16x32_bf16 v[108:111], v[132:135], v[184:187], v[108:111]
	v_mfma_f32_16x16x32_bf16 v[104:107], v[140:143], v[184:187], v[104:107]
	v_mfma_f32_16x16x32_bf16 v[92:95], v[132:135], v[192:195], v[92:95]
	v_mfma_f32_16x16x32_bf16 v[88:91], v[140:143], v[192:195], v[88:91]
	v_mfma_f32_16x16x32_bf16 v[76:79], v[132:135], v[200:203], v[76:79]
	v_mfma_f32_16x16x32_bf16 v[72:75], v[140:143], v[200:203], v[72:75]
	s_setprio 0
	s_barrier
	s_add_i32 s39, s80, s33
	v_lshl_add_u64 v[176:177], s[6:7], 0, v[150:151]
	s_mov_b32 m0, s39
	ds_read_b128 v[204:207], v183
	ds_read_b128 v[210:213], v183 offset:1024
	ds_read_b128 v[214:217], v183 offset:2048
	ds_read_b128 v[218:221], v183 offset:3072
	global_load_lds_dwordx4 v[176:177], off
	v_lshl_add_u64 v[222:223], s[6:7], 0, v[154:155]
	s_add_i32 m0, s39, 0x2000
	s_nop 0
	global_load_lds_dwordx4 v[222:223], off
	s_barrier
	s_waitcnt lgkmcnt(0)
	s_setprio 1
	s_waitcnt lgkmcnt(0)
	v_mfma_f32_16x16x32_bf16 v[116:119], v[204:207], v[144:147], v[116:119]
	v_mfma_f32_16x16x32_bf16 v[112:115], v[214:217], v[144:147], v[112:115]
	v_mfma_f32_16x16x32_bf16 v[100:103], v[204:207], v[172:175], v[100:103]
	v_mfma_f32_16x16x32_bf16 v[96:99], v[214:217], v[172:175], v[96:99]
	v_mfma_f32_16x16x32_bf16 v[84:87], v[204:207], v[188:191], v[84:87]
	v_mfma_f32_16x16x32_bf16 v[80:83], v[214:217], v[188:191], v[80:83]
	v_mfma_f32_16x16x32_bf16 v[68:71], v[204:207], v[196:199], v[68:71]
	v_mfma_f32_16x16x32_bf16 v[64:67], v[214:217], v[196:199], v[64:67]
	v_mfma_f32_16x16x32_bf16 v[116:119], v[210:213], v[168:171], v[116:119]
	v_mfma_f32_16x16x32_bf16 v[112:115], v[218:221], v[168:171], v[112:115]
	v_mfma_f32_16x16x32_bf16 v[100:103], v[210:213], v[184:187], v[100:103]
	v_mfma_f32_16x16x32_bf16 v[96:99], v[218:221], v[184:187], v[96:99]
	v_mfma_f32_16x16x32_bf16 v[84:87], v[210:213], v[192:195], v[84:87]
	v_mfma_f32_16x16x32_bf16 v[80:83], v[218:221], v[192:195], v[80:83]
	v_mfma_f32_16x16x32_bf16 v[68:71], v[210:213], v[200:203], v[68:71]
	v_mfma_f32_16x16x32_bf16 v[64:67], v[218:221], v[200:203], v[64:67]
	s_setprio 0
	s_mov_b32 m0, s44
	v_lshl_add_u64 v[224:225], s[8:9], 0, v[148:149]
	s_barrier
	ds_read_b128 v[144:147], v182 offset:16384
	ds_read_b128 v[168:171], v182 offset:17408
	ds_read_b128 v[172:175], v182 offset:18432
	ds_read_b128 v[184:187], v182 offset:19456
	ds_read_b128 v[188:191], v182 offset:20480
	ds_read_b128 v[192:195], v182 offset:21504
	ds_read_b128 v[196:199], v182 offset:22528
	ds_read_b128 v[200:203], v182 offset:23552
	global_load_lds_dwordx4 v[224:225], off
	v_lshl_add_u64 v[226:227], s[8:9], 0, v[152:153]
	s_mov_b32 m0, s45
	s_nop 0
	global_load_lds_dwordx4 v[226:227], off
	s_waitcnt vmcnt(10)
	s_barrier
	s_waitcnt lgkmcnt(0)
	s_setprio 1
	s_waitcnt lgkmcnt(0)
	v_mfma_f32_16x16x32_bf16 v[60:63], v[128:131], v[144:147], v[60:63]
	v_mfma_f32_16x16x32_bf16 v[56:59], v[136:139], v[144:147], v[56:59]
	v_mfma_f32_16x16x32_bf16 v[44:47], v[128:131], v[172:175], v[44:47]
	v_mfma_f32_16x16x32_bf16 v[40:43], v[136:139], v[172:175], v[40:43]
	v_mfma_f32_16x16x32_bf16 v[28:31], v[128:131], v[188:191], v[28:31]
	v_mfma_f32_16x16x32_bf16 v[24:27], v[136:139], v[188:191], v[24:27]
	v_mfma_f32_16x16x32_bf16 v[12:15], v[128:131], v[196:199], v[12:15]
	v_mfma_f32_16x16x32_bf16 v[8:11], v[136:139], v[196:199], v[8:11]
	v_mfma_f32_16x16x32_bf16 v[60:63], v[132:135], v[168:171], v[60:63]
	v_mfma_f32_16x16x32_bf16 v[56:59], v[140:143], v[168:171], v[56:59]
	v_mfma_f32_16x16x32_bf16 v[44:47], v[132:135], v[184:187], v[44:47]
	v_mfma_f32_16x16x32_bf16 v[40:43], v[140:143], v[184:187], v[40:43]
	v_mfma_f32_16x16x32_bf16 v[28:31], v[132:135], v[192:195], v[28:31]
	v_mfma_f32_16x16x32_bf16 v[24:27], v[140:143], v[192:195], v[24:27]
	v_mfma_f32_16x16x32_bf16 v[12:15], v[132:135], v[200:203], v[12:15]
	v_mfma_f32_16x16x32_bf16 v[8:11], v[140:143], v[200:203], v[8:11]
	s_setprio 0
	s_barrier
	s_add_u32 s78, s6, 0x80000
	s_addc_u32 s79, s7, 0
	s_add_i32 s39, s81, s33
	v_lshl_add_u64 v[128:129], s[78:79], 0, v[150:151]
	s_mov_b32 m0, s39
	s_nop 0
	global_load_lds_dwordx4 v[128:129], off
	v_lshl_add_u64 v[128:129], s[78:79], 0, v[154:155]
	s_add_i32 m0, s39, 0x2000
	s_nop 0
	global_load_lds_dwordx4 v[128:129], off
	s_add_i32 s39, 0, 0x18000
	v_add_u32_e32 v140, s39, v180
	ds_read_b128 v[128:131], v140
	ds_read_b128 v[132:135], v140 offset:1024
	ds_read_b128 v[136:139], v140 offset:2048
	ds_read_b128 v[140:143], v140 offset:3072
	s_waitcnt vmcnt(6)
	s_barrier
	s_setprio 1
	v_mfma_f32_16x16x32_bf16 v[52:55], v[204:207], v[144:147], v[52:55]
	v_mfma_f32_16x16x32_bf16 v[48:51], v[214:217], v[144:147], v[48:51]
	v_mfma_f32_16x16x32_bf16 v[36:39], v[204:207], v[172:175], v[36:39]
	v_mfma_f32_16x16x32_bf16 v[32:35], v[214:217], v[172:175], v[32:35]
	v_mfma_f32_16x16x32_bf16 v[20:23], v[204:207], v[188:191], v[20:23]
	v_mfma_f32_16x16x32_bf16 v[16:19], v[214:217], v[188:191], v[16:19]
	v_mfma_f32_16x16x32_bf16 v[4:7], v[204:207], v[196:199], v[4:7]
	v_mfma_f32_16x16x32_bf16 v[0:3], v[214:217], v[196:199], v[0:3]
	v_mfma_f32_16x16x32_bf16 v[52:55], v[210:213], v[168:171], v[52:55]
	v_mfma_f32_16x16x32_bf16 v[48:51], v[218:221], v[168:171], v[48:51]
	v_mfma_f32_16x16x32_bf16 v[36:39], v[210:213], v[184:187], v[36:39]
	v_mfma_f32_16x16x32_bf16 v[32:35], v[218:221], v[184:187], v[32:35]
	v_mfma_f32_16x16x32_bf16 v[20:23], v[210:213], v[192:195], v[20:23]
	v_mfma_f32_16x16x32_bf16 v[16:19], v[218:221], v[192:195], v[16:19]
	v_mfma_f32_16x16x32_bf16 v[4:7], v[210:213], v[200:203], v[4:7]
	v_mfma_f32_16x16x32_bf16 v[0:3], v[218:221], v[200:203], v[0:3]
	s_setprio 0
	s_barrier
	s_add_u32 s8, s8, 0x80000
	s_addc_u32 s9, s9, 0
	s_mov_b32 m0, s51
	v_lshl_add_u64 v[204:205], s[8:9], 0, v[148:149]
	ds_read_b128 v[144:147], v182 offset:32768
	ds_read_b128 v[168:171], v182 offset:33792
	ds_read_b128 v[172:175], v182 offset:34816
	ds_read_b128 v[184:187], v182 offset:35840
	ds_read_b128 v[188:191], v182 offset:36864
	ds_read_b128 v[192:195], v182 offset:37888
	ds_read_b128 v[196:199], v182 offset:38912
	ds_read_b128 v[200:203], v182 offset:39936
	global_load_lds_dwordx4 v[204:205], off
	v_lshl_add_u64 v[204:205], s[8:9], 0, v[152:153]
	s_mov_b32 m0, s55
	s_nop 0
	global_load_lds_dwordx4 v[204:205], off
	s_waitcnt lgkmcnt(8)
	s_barrier
	s_waitcnt lgkmcnt(0)
	s_setprio 1
	s_waitcnt lgkmcnt(0)
	v_mfma_f32_16x16x32_bf16 v[124:127], v[128:131], v[144:147], v[124:127]
	v_mfma_f32_16x16x32_bf16 v[120:123], v[136:139], v[144:147], v[120:123]
	v_mfma_f32_16x16x32_bf16 v[108:111], v[128:131], v[172:175], v[108:111]
	v_mfma_f32_16x16x32_bf16 v[104:107], v[136:139], v[172:175], v[104:107]
	v_mfma_f32_16x16x32_bf16 v[92:95], v[128:131], v[188:191], v[92:95]
	v_mfma_f32_16x16x32_bf16 v[88:91], v[136:139], v[188:191], v[88:91]
	v_mfma_f32_16x16x32_bf16 v[76:79], v[128:131], v[196:199], v[76:79]
	v_mfma_f32_16x16x32_bf16 v[72:75], v[136:139], v[196:199], v[72:75]
	v_mfma_f32_16x16x32_bf16 v[124:127], v[132:135], v[168:171], v[124:127]
	v_mfma_f32_16x16x32_bf16 v[120:123], v[140:143], v[168:171], v[120:123]
	v_mfma_f32_16x16x32_bf16 v[108:111], v[132:135], v[184:187], v[108:111]
	v_mfma_f32_16x16x32_bf16 v[104:107], v[140:143], v[184:187], v[104:107]
	v_mfma_f32_16x16x32_bf16 v[92:95], v[132:135], v[192:195], v[92:95]
	v_mfma_f32_16x16x32_bf16 v[88:91], v[140:143], v[192:195], v[88:91]
	v_mfma_f32_16x16x32_bf16 v[76:79], v[132:135], v[200:203], v[76:79]
	v_mfma_f32_16x16x32_bf16 v[72:75], v[140:143], v[200:203], v[72:75]
	s_setprio 0
	s_barrier
	s_add_i32 s8, 0, 0x1c000
	s_add_i32 s9, s39, s33
	v_add_u32_e32 v156, s8, v180
	v_lshl_add_u64 v[176:177], v[176:177], 0, s[24:25]
	s_mov_b32 m0, s9
	ds_read_b128 v[204:207], v156
	ds_read_b128 v[210:213], v156 offset:1024
	ds_read_b128 v[214:217], v156 offset:2048
	ds_read_b128 v[218:221], v156 offset:3072
	global_load_lds_dwordx4 v[176:177], off
	v_lshl_add_u64 v[176:177], v[222:223], 0, s[24:25]
	s_add_i32 m0, s9, 0x2000
	s_nop 0
	global_load_lds_dwordx4 v[176:177], off
	s_barrier
	s_waitcnt lgkmcnt(0)
	s_setprio 1
	s_waitcnt lgkmcnt(0)
	v_mfma_f32_16x16x32_bf16 v[116:119], v[204:207], v[144:147], v[116:119]
	v_mfma_f32_16x16x32_bf16 v[112:115], v[214:217], v[144:147], v[112:115]
	v_mfma_f32_16x16x32_bf16 v[100:103], v[204:207], v[172:175], v[100:103]
	v_mfma_f32_16x16x32_bf16 v[96:99], v[214:217], v[172:175], v[96:99]
	v_mfma_f32_16x16x32_bf16 v[84:87], v[204:207], v[188:191], v[84:87]
	v_mfma_f32_16x16x32_bf16 v[80:83], v[214:217], v[188:191], v[80:83]
	v_mfma_f32_16x16x32_bf16 v[68:71], v[204:207], v[196:199], v[68:71]
	v_mfma_f32_16x16x32_bf16 v[64:67], v[214:217], v[196:199], v[64:67]
	v_mfma_f32_16x16x32_bf16 v[116:119], v[210:213], v[168:171], v[116:119]
	v_mfma_f32_16x16x32_bf16 v[112:115], v[218:221], v[168:171], v[112:115]
	v_mfma_f32_16x16x32_bf16 v[100:103], v[210:213], v[184:187], v[100:103]
	v_mfma_f32_16x16x32_bf16 v[96:99], v[218:221], v[184:187], v[96:99]
	v_mfma_f32_16x16x32_bf16 v[84:87], v[210:213], v[192:195], v[84:87]
	v_mfma_f32_16x16x32_bf16 v[80:83], v[218:221], v[192:195], v[80:83]
	v_mfma_f32_16x16x32_bf16 v[68:71], v[210:213], v[200:203], v[68:71]
	v_mfma_f32_16x16x32_bf16 v[64:67], v[218:221], v[200:203], v[64:67]
	s_setprio 0
	s_mov_b32 m0, s83
	v_lshl_add_u64 v[176:177], v[224:225], 0, s[24:25]
	s_barrier
	ds_read_b128 v[144:147], v182 offset:49152
	ds_read_b128 v[168:171], v182 offset:50176
	ds_read_b128 v[172:175], v182 offset:51200
	ds_read_b128 v[184:187], v182 offset:52224
	ds_read_b128 v[188:191], v182 offset:53248
	ds_read_b128 v[192:195], v182 offset:54272
	ds_read_b128 v[196:199], v182 offset:55296
	ds_read_b128 v[200:203], v182 offset:56320
	global_load_lds_dwordx4 v[176:177], off
	v_lshl_add_u64 v[176:177], v[226:227], 0, s[24:25]
	s_mov_b32 m0, s91
	s_nop 0
	global_load_lds_dwordx4 v[176:177], off
	s_waitcnt vmcnt(10)
	s_barrier
	s_waitcnt lgkmcnt(0)
	s_setprio 1
	s_waitcnt lgkmcnt(0)
	v_mfma_f32_16x16x32_bf16 v[60:63], v[128:131], v[144:147], v[60:63]
	v_mfma_f32_16x16x32_bf16 v[56:59], v[136:139], v[144:147], v[56:59]
	v_mfma_f32_16x16x32_bf16 v[44:47], v[128:131], v[172:175], v[44:47]
	v_mfma_f32_16x16x32_bf16 v[40:43], v[136:139], v[172:175], v[40:43]
	v_mfma_f32_16x16x32_bf16 v[28:31], v[128:131], v[188:191], v[28:31]
	v_mfma_f32_16x16x32_bf16 v[24:27], v[136:139], v[188:191], v[24:27]
	v_mfma_f32_16x16x32_bf16 v[12:15], v[128:131], v[196:199], v[12:15]
	v_mfma_f32_16x16x32_bf16 v[8:11], v[136:139], v[196:199], v[8:11]
	v_mfma_f32_16x16x32_bf16 v[60:63], v[132:135], v[168:171], v[60:63]
	v_mfma_f32_16x16x32_bf16 v[56:59], v[140:143], v[168:171], v[56:59]
	v_mfma_f32_16x16x32_bf16 v[44:47], v[132:135], v[184:187], v[44:47]
	v_mfma_f32_16x16x32_bf16 v[40:43], v[140:143], v[184:187], v[40:43]
	v_mfma_f32_16x16x32_bf16 v[28:31], v[132:135], v[192:195], v[28:31]
	v_mfma_f32_16x16x32_bf16 v[24:27], v[140:143], v[192:195], v[24:27]
	v_mfma_f32_16x16x32_bf16 v[12:15], v[132:135], v[200:203], v[12:15]
	v_mfma_f32_16x16x32_bf16 v[8:11], v[140:143], v[200:203], v[8:11]
	s_setprio 0
	s_barrier
	s_add_u32 s6, s6, 0x80080
	s_addc_u32 s7, s7, 0
	s_add_i32 s8, s8, s33
	v_lshl_add_u64 v[128:129], s[6:7], 0, v[150:151]
	s_mov_b32 m0, s8
	s_nop 0
	global_load_lds_dwordx4 v[128:129], off
	v_lshl_add_u64 v[128:129], s[6:7], 0, v[154:155]
	s_add_i32 m0, s8, 0x2000
	s_nop 0
	global_load_lds_dwordx4 v[128:129], off
	ds_read_b128 v[128:131], v181
	ds_read_b128 v[132:135], v181 offset:1024
	ds_read_b128 v[136:139], v181 offset:2048
	ds_read_b128 v[140:143], v181 offset:3072
	s_waitcnt vmcnt(6)
	s_barrier
	s_setprio 1
	s_waitcnt lgkmcnt(0)
	v_mfma_f32_16x16x32_bf16 v[52:55], v[204:207], v[144:147], v[52:55]
	v_mfma_f32_16x16x32_bf16 v[48:51], v[214:217], v[144:147], v[48:51]
	v_mfma_f32_16x16x32_bf16 v[36:39], v[204:207], v[172:175], v[36:39]
	v_mfma_f32_16x16x32_bf16 v[32:35], v[214:217], v[172:175], v[32:35]
	v_mfma_f32_16x16x32_bf16 v[20:23], v[204:207], v[188:191], v[20:23]
	v_mfma_f32_16x16x32_bf16 v[16:19], v[214:217], v[188:191], v[16:19]
	v_mfma_f32_16x16x32_bf16 v[4:7], v[204:207], v[196:199], v[4:7]
	v_mfma_f32_16x16x32_bf16 v[0:3], v[214:217], v[196:199], v[0:3]
	v_mfma_f32_16x16x32_bf16 v[52:55], v[210:213], v[168:171], v[52:55]
	v_mfma_f32_16x16x32_bf16 v[48:51], v[218:221], v[168:171], v[48:51]
	v_mfma_f32_16x16x32_bf16 v[36:39], v[210:213], v[184:187], v[36:39]
	v_mfma_f32_16x16x32_bf16 v[32:35], v[218:221], v[184:187], v[32:35]
	v_mfma_f32_16x16x32_bf16 v[20:23], v[210:213], v[192:195], v[20:23]
	v_mfma_f32_16x16x32_bf16 v[16:19], v[218:221], v[192:195], v[16:19]
	v_mfma_f32_16x16x32_bf16 v[4:7], v[210:213], v[200:203], v[4:7]
	v_mfma_f32_16x16x32_bf16 v[0:3], v[218:221], v[200:203], v[0:3]
	s_setprio 0
	s_add_i32 s37, s37, 2
	s_add_u32 s4, s4, 0x100
	s_addc_u32 s5, s5, 0
	s_add_u32 s35, s35, 0x100
	s_addc_u32 s36, s36, 0
	s_cmp_gt_u32 s37, 29
	s_barrier
	s_cbranch_scc0 .LBB0_262
	v_mov_b32_e32 v185, v179
	v_mov_b32_e32 v184, v178
	s_cmp_lt_i32 s90, 33
	s_mov_b64 s[4:5], -1
	s_cbranch_scc0 .LBB0_589
	s_cmp_gt_i32 s82, 3
	s_cbranch_scc0 .LBB0_586
	s_cmp_gt_u32 s82, 7
	s_cbranch_scc0 .LBB0_551
	s_cmp_gt_u32 s82, 15
	s_cbranch_scc0 .LBB0_548
	s_cmp_gt_u32 s82, 23
	s_cbranch_scc0 .LBB0_545
	s_cmp_gt_u32 s82, 27
	s_cbranch_scc0 .LBB0_486
	s_cmp_gt_u32 s82, 31
	s_cbranch_scc0 .LBB0_315
	s_cmp_gt_u32 s82, 35
	s_cbranch_scc0 .LBB0_280
	s_cmp_gt_u32 s82, 39
	s_cbranch_scc0 .LBB0_277
	s_lshl_b32 s4, s90, 8
	s_add_i32 s4, s4, s57
	v_lshl_add_u32 v128, v185, 3, s59
	v_add_u32_e32 v132, s4, v184
	v_ashrrev_i32_e32 v129, 31, v128
	v_mad_i64_i32 v[130:131], s[4:5], v132, s28, 0
	s_cmp_gt_u32 s82, 41
	s_mov_b64 s[4:5], -1
	v_lshl_add_u64 v[130:131], s[0:1], 0, v[130:131]
	v_lshlrev_b64 v[128:129], 1, v[128:129]
	v_add_u32_e32 v138, 16, v132
	v_add_u32_e32 v137, 32, v132
	v_add_u32_e32 v136, 48, v132
	v_add_u32_e32 v135, 0x80, v132
	v_add_u32_e32 v134, 0x90, v132
	v_add_u32_e32 v133, 0xa0, v132
	v_add_u32_e32 v132, 0xb0, v132
	s_cbranch_scc0 .LBB0_274
	s_lshl_b32 s20, s82, 8
	s_lshl_b64 s[4:5], s[20:21], 1
	v_lshl_add_u64 v[144:145], v[130:131], 0, s[4:5]
	v_cvt_pk_bf16_f32 v140, v124, v125
	v_cvt_pk_bf16_f32 v141, v126, v127
	v_cvt_pk_bf16_f32 v142, v120, v121
	v_cvt_pk_bf16_f32 v143, v122, v123
	v_lshl_add_u64 v[144:145], v[144:145], 0, v[128:129]
	global_store_dwordx4 v[144:145], v[140:143], off
	s_nop 1
	v_cvt_pk_bf16_f32 v140, v116, v117
	v_cvt_pk_bf16_f32 v141, v118, v119
	v_cvt_pk_bf16_f32 v142, v112, v113
	v_cvt_pk_bf16_f32 v143, v114, v115
	global_store_dwordx4 v[144:145], v[140:143], off offset:256
	v_mov_b64_e32 v[144:145], s[0:1]
	v_mad_i64_i32 v[146:147], s[6:7], v138, s28, v[144:145]
	v_lshl_add_u64 v[146:147], v[146:147], 0, s[4:5]
	v_cvt_pk_bf16_f32 v140, v108, v109
	v_cvt_pk_bf16_f32 v141, v110, v111
	v_cvt_pk_bf16_f32 v142, v104, v105
	v_cvt_pk_bf16_f32 v143, v106, v107
	v_lshl_add_u64 v[146:147], v[146:147], 0, v[128:129]
	global_store_dwordx4 v[146:147], v[140:143], off
	s_nop 1
	v_cvt_pk_bf16_f32 v140, v100, v101
	v_cvt_pk_bf16_f32 v141, v102, v103
	v_cvt_pk_bf16_f32 v142, v96, v97
	v_cvt_pk_bf16_f32 v143, v98, v99
	global_store_dwordx4 v[146:147], v[140:143], off offset:256
	v_mad_i64_i32 v[146:147], s[6:7], v137, s28, v[144:145]
	v_lshl_add_u64 v[146:147], v[146:147], 0, s[4:5]
	v_cvt_pk_bf16_f32 v140, v92, v93
	v_cvt_pk_bf16_f32 v141, v94, v95
	v_cvt_pk_bf16_f32 v142, v88, v89
	v_cvt_pk_bf16_f32 v143, v90, v91
	v_lshl_add_u64 v[146:147], v[146:147], 0, v[128:129]
	global_store_dwordx4 v[146:147], v[140:143], off
	s_nop 1
	v_cvt_pk_bf16_f32 v140, v84, v85
	v_cvt_pk_bf16_f32 v141, v86, v87
	v_cvt_pk_bf16_f32 v142, v80, v81
	v_cvt_pk_bf16_f32 v143, v82, v83
	global_store_dwordx4 v[146:147], v[140:143], off offset:256
	v_mad_i64_i32 v[146:147], s[6:7], v136, s28, v[144:145]
	v_lshl_add_u64 v[146:147], v[146:147], 0, s[4:5]
	v_cvt_pk_bf16_f32 v140, v76, v77
	v_cvt_pk_bf16_f32 v141, v78, v79
	v_cvt_pk_bf16_f32 v142, v72, v73
	v_cvt_pk_bf16_f32 v143, v74, v75
	v_lshl_add_u64 v[146:147], v[146:147], 0, v[128:129]
	global_store_dwordx4 v[146:147], v[140:143], off
	s_nop 1
	v_cvt_pk_bf16_f32 v140, v68, v69
	v_cvt_pk_bf16_f32 v141, v70, v71
	v_cvt_pk_bf16_f32 v142, v64, v65
	v_cvt_pk_bf16_f32 v143, v66, v67
	global_store_dwordx4 v[146:147], v[140:143], off offset:256
	v_mad_i64_i32 v[146:147], s[6:7], v135, s28, v[144:145]
	v_lshl_add_u64 v[146:147], v[146:147], 0, s[4:5]
	v_cvt_pk_bf16_f32 v140, v60, v61
	v_cvt_pk_bf16_f32 v141, v62, v63
	v_cvt_pk_bf16_f32 v142, v56, v57
	v_cvt_pk_bf16_f32 v143, v58, v59
	v_lshl_add_u64 v[146:147], v[146:147], 0, v[128:129]
	global_store_dwordx4 v[146:147], v[140:143], off
	s_nop 1
	v_cvt_pk_bf16_f32 v140, v52, v53
	v_cvt_pk_bf16_f32 v141, v54, v55
	v_cvt_pk_bf16_f32 v142, v48, v49
	v_cvt_pk_bf16_f32 v143, v50, v51
	global_store_dwordx4 v[146:147], v[140:143], off offset:256
	v_mad_i64_i32 v[146:147], s[6:7], v134, s28, v[144:145]
	v_lshl_add_u64 v[146:147], v[146:147], 0, s[4:5]
	v_cvt_pk_bf16_f32 v140, v44, v45
	v_cvt_pk_bf16_f32 v141, v46, v47
	v_cvt_pk_bf16_f32 v142, v40, v41
	v_cvt_pk_bf16_f32 v143, v42, v43
	v_lshl_add_u64 v[146:147], v[146:147], 0, v[128:129]
	global_store_dwordx4 v[146:147], v[140:143], off
	s_nop 1
	v_cvt_pk_bf16_f32 v140, v36, v37
	v_cvt_pk_bf16_f32 v141, v38, v39
	v_cvt_pk_bf16_f32 v142, v32, v33
	v_cvt_pk_bf16_f32 v143, v34, v35
	global_store_dwordx4 v[146:147], v[140:143], off offset:256
	v_mad_i64_i32 v[146:147], s[6:7], v133, s28, v[144:145]
	v_lshl_add_u64 v[146:147], v[146:147], 0, s[4:5]
	v_cvt_pk_bf16_f32 v140, v28, v29
	v_cvt_pk_bf16_f32 v141, v30, v31
	v_cvt_pk_bf16_f32 v142, v24, v25
	v_cvt_pk_bf16_f32 v143, v26, v27
	v_lshl_add_u64 v[146:147], v[146:147], 0, v[128:129]
	v_mad_i64_i32 v[144:145], s[6:7], v132, s28, v[144:145]
	global_store_dwordx4 v[146:147], v[140:143], off
	v_lshl_add_u64 v[144:145], v[144:145], 0, s[4:5]
	v_lshl_add_u64 v[144:145], v[144:145], 0, v[128:129]
	v_cvt_pk_bf16_f32 v140, v20, v21
	v_cvt_pk_bf16_f32 v141, v22, v23
	v_cvt_pk_bf16_f32 v142, v16, v17
	v_cvt_pk_bf16_f32 v143, v18, v19
	global_store_dwordx4 v[146:147], v[140:143], off offset:256
	s_mov_b64 s[4:5], 0
	s_nop 0
	v_cvt_pk_bf16_f32 v140, v12, v13
	v_cvt_pk_bf16_f32 v141, v14, v15
	v_cvt_pk_bf16_f32 v142, v8, v9
	v_cvt_pk_bf16_f32 v143, v10, v11
	global_store_dwordx4 v[144:145], v[140:143], off
	s_nop 1
	v_cvt_pk_bf16_f32 v140, v4, v5
	v_cvt_pk_bf16_f32 v141, v6, v7
	v_cvt_pk_bf16_f32 v142, v0, v1
	v_cvt_pk_bf16_f32 v143, v2, v3
	global_store_dwordx4 v[144:145], v[140:143], off offset:256

.LBB0_973:
	s_add_u32 s42, s16, 0x100
	v_mov_b32_e32 v0, 0
	s_addc_u32 s43, s17, 0
	s_mov_b32 s44, -2
	v_mov_b32_e32 v1, v0
	v_mov_b32_e32 v2, v0
	v_mov_b32_e32 v3, v0
	v_mov_b32_e32 v4, v0
	v_mov_b32_e32 v5, v0
	v_mov_b32_e32 v6, v0
	v_mov_b32_e32 v7, v0
	v_mov_b32_e32 v8, v0
	v_mov_b32_e32 v9, v0
	v_mov_b32_e32 v10, v0
	v_mov_b32_e32 v11, v0
	v_mov_b32_e32 v12, v0
	v_mov_b32_e32 v13, v0
	v_mov_b32_e32 v14, v0
	v_mov_b32_e32 v15, v0
	v_mov_b32_e32 v24, v0
	v_mov_b32_e32 v25, v0
	v_mov_b32_e32 v26, v0
	v_mov_b32_e32 v27, v0
	v_mov_b32_e32 v28, v0
	v_mov_b32_e32 v29, v0
	v_mov_b32_e32 v30, v0
	v_mov_b32_e32 v31, v0
	v_mov_b32_e32 v40, v0
	v_mov_b32_e32 v41, v0
	v_mov_b32_e32 v42, v0
	v_mov_b32_e32 v43, v0
	v_mov_b32_e32 v44, v0
	v_mov_b32_e32 v45, v0
	v_mov_b32_e32 v46, v0
	v_mov_b32_e32 v47, v0
	v_mov_b32_e32 v16, v0
	v_mov_b32_e32 v17, v0
	v_mov_b32_e32 v18, v0
	v_mov_b32_e32 v19, v0
	v_mov_b32_e32 v20, v0
	v_mov_b32_e32 v21, v0
	v_mov_b32_e32 v22, v0
	v_mov_b32_e32 v23, v0
	v_mov_b32_e32 v32, v0
	v_mov_b32_e32 v33, v0
	v_mov_b32_e32 v34, v0
	v_mov_b32_e32 v35, v0
	v_mov_b32_e32 v36, v0
	v_mov_b32_e32 v37, v0
	v_mov_b32_e32 v38, v0
	v_mov_b32_e32 v39, v0
	v_mov_b32_e32 v48, v0
	v_mov_b32_e32 v49, v0
	v_mov_b32_e32 v50, v0
	v_mov_b32_e32 v51, v0
	v_mov_b32_e32 v52, v0
	v_mov_b32_e32 v53, v0
	v_mov_b32_e32 v54, v0
	v_mov_b32_e32 v55, v0
	v_mov_b32_e32 v56, v0
	v_mov_b32_e32 v57, v0
	v_mov_b32_e32 v58, v0
	v_mov_b32_e32 v59, v0
	v_mov_b32_e32 v60, v0
	v_mov_b32_e32 v61, v0
	v_mov_b32_e32 v62, v0
	v_mov_b32_e32 v63, v0
	v_mov_b32_e32 v64, v0
	v_mov_b32_e32 v65, v0
	v_mov_b32_e32 v66, v0
	v_mov_b32_e32 v67, v0
	v_mov_b32_e32 v68, v0
	v_mov_b32_e32 v69, v0
	v_mov_b32_e32 v70, v0
	v_mov_b32_e32 v71, v0
	v_mov_b32_e32 v72, v0
	v_mov_b32_e32 v73, v0
	v_mov_b32_e32 v74, v0
	v_mov_b32_e32 v75, v0
	v_mov_b32_e32 v76, v0
	v_mov_b32_e32 v77, v0
	v_mov_b32_e32 v78, v0
	v_mov_b32_e32 v79, v0
	v_mov_b32_e32 v88, v0
	v_mov_b32_e32 v89, v0
	v_mov_b32_e32 v90, v0
	v_mov_b32_e32 v91, v0
	v_mov_b32_e32 v92, v0
	v_mov_b32_e32 v93, v0
	v_mov_b32_e32 v94, v0
	v_mov_b32_e32 v95, v0
	v_mov_b32_e32 v104, v0
	v_mov_b32_e32 v105, v0
	v_mov_b32_e32 v106, v0
	v_mov_b32_e32 v107, v0
	v_mov_b32_e32 v108, v0
	v_mov_b32_e32 v109, v0
	v_mov_b32_e32 v110, v0
	v_mov_b32_e32 v111, v0
	v_mov_b32_e32 v80, v0
	v_mov_b32_e32 v81, v0
	v_mov_b32_e32 v82, v0
	v_mov_b32_e32 v83, v0
	v_mov_b32_e32 v84, v0
	v_mov_b32_e32 v85, v0
	v_mov_b32_e32 v86, v0
	v_mov_b32_e32 v87, v0
	v_mov_b32_e32 v96, v0
	v_mov_b32_e32 v97, v0
	v_mov_b32_e32 v98, v0
	v_mov_b32_e32 v99, v0
	v_mov_b32_e32 v100, v0
	v_mov_b32_e32 v101, v0
	v_mov_b32_e32 v102, v0
	v_mov_b32_e32 v103, v0
	v_mov_b32_e32 v112, v0
	v_mov_b32_e32 v113, v0
	v_mov_b32_e32 v114, v0
	v_mov_b32_e32 v115, v0
	v_mov_b32_e32 v116, v0
	v_mov_b32_e32 v117, v0
	v_mov_b32_e32 v118, v0
	v_mov_b32_e32 v119, v0
	v_mov_b32_e32 v120, v0
	v_mov_b32_e32 v121, v0
	v_mov_b32_e32 v122, v0
	v_mov_b32_e32 v123, v0
	v_mov_b32_e32 v124, v0
	v_mov_b32_e32 v125, v0
	v_mov_b32_e32 v126, v0
	v_mov_b32_e32 v127, v0
	ds_read_b128 v[150:153], v147
	ds_read_b128 v[154:157], v147 offset:1024
	ds_read_b128 v[158:161], v147 offset:2048
	ds_read_b128 v[162:165], v147 offset:3072
.LBB0_974:
	s_add_u32 s16, s14, 0x100
	s_addc_u32 s17, s15, 0
	s_cmp_eq_u32 s44, 52
	s_cselect_b32 s21, s3, s17
	s_cselect_b32 s20, s2, s16
	s_cselect_b32 s19, s5, s43
	s_cselect_b32 s18, s4, s42
	v_lshl_add_u64 v[198:199], s[14:15], 0, v[136:137]
	s_add_i32 m0, s24, 0xc000
	ds_read_b128 v[166:169], v148
	ds_read_b128 v[170:173], v148 offset:1024
	ds_read_b128 v[174:177], v148 offset:2048
	ds_read_b128 v[178:181], v148 offset:3072
	ds_read_b128 v[182:185], v148 offset:4096
	ds_read_b128 v[186:189], v148 offset:5120
	ds_read_b128 v[190:193], v148 offset:6144
	ds_read_b128 v[194:197], v148 offset:7168
	global_load_lds_dwordx4 v[198:199], off
	v_lshl_add_u64 v[198:199], s[14:15], 0, v[138:139]
	s_add_i32 m0, s24, 0xe000
	s_nop 0
	global_load_lds_dwordx4 v[198:199], off
	s_waitcnt lgkmcnt(8)
	s_barrier
	s_waitcnt lgkmcnt(0)
	s_setprio 1
	s_waitcnt lgkmcnt(0)
	v_mfma_f32_16x16x32_bf16 v[124:127], v[150:153], v[166:169], v[124:127]
	v_mfma_f32_16x16x32_bf16 v[120:123], v[158:161], v[166:169], v[120:123]
	v_mfma_f32_16x16x32_bf16 v[116:119], v[150:153], v[174:177], v[116:119]
	v_mfma_f32_16x16x32_bf16 v[112:115], v[158:161], v[174:177], v[112:115]
	v_mfma_f32_16x16x32_bf16 v[100:103], v[150:153], v[182:185], v[100:103]
	v_mfma_f32_16x16x32_bf16 v[96:99], v[158:161], v[182:185], v[96:99]
	v_mfma_f32_16x16x32_bf16 v[84:87], v[150:153], v[190:193], v[84:87]
	v_mfma_f32_16x16x32_bf16 v[80:83], v[158:161], v[190:193], v[80:83]
	v_mfma_f32_16x16x32_bf16 v[124:127], v[154:157], v[170:173], v[124:127]
	v_mfma_f32_16x16x32_bf16 v[120:123], v[162:165], v[170:173], v[120:123]
	v_mfma_f32_16x16x32_bf16 v[116:119], v[154:157], v[178:181], v[116:119]
	v_mfma_f32_16x16x32_bf16 v[112:115], v[162:165], v[178:181], v[112:115]
	v_mfma_f32_16x16x32_bf16 v[100:103], v[154:157], v[186:189], v[100:103]
	v_mfma_f32_16x16x32_bf16 v[96:99], v[162:165], v[186:189], v[96:99]
	v_mfma_f32_16x16x32_bf16 v[84:87], v[154:157], v[194:197], v[84:87]
	v_mfma_f32_16x16x32_bf16 v[80:83], v[162:165], v[194:197], v[80:83]
	s_setprio 0
	s_barrier
	s_add_i32 s14, s35, s23
	v_lshl_add_u64 v[206:207], s[18:19], 0, v[130:131]
	s_mov_b32 m0, s14
	ds_read_b128 v[198:201], v149
	ds_read_b128 v[202:205], v149 offset:1024
	ds_read_b128 v[210:213], v149 offset:2048
	ds_read_b128 v[214:217], v149 offset:3072
	global_load_lds_dwordx4 v[206:207], off
	v_lshl_add_u64 v[218:219], s[18:19], 0, v[134:135]
	s_add_i32 m0, s14, 0x2000
	s_nop 0
	global_load_lds_dwordx4 v[218:219], off
	s_barrier
	s_waitcnt lgkmcnt(0)
	s_setprio 1
	s_waitcnt lgkmcnt(0)
	v_mfma_f32_16x16x32_bf16 v[108:111], v[198:201], v[166:169], v[108:111]
	v_mfma_f32_16x16x32_bf16 v[104:107], v[210:213], v[166:169], v[104:107]
	v_mfma_f32_16x16x32_bf16 v[92:95], v[198:201], v[174:177], v[92:95]
	v_mfma_f32_16x16x32_bf16 v[88:91], v[210:213], v[174:177], v[88:91]
	v_mfma_f32_16x16x32_bf16 v[76:79], v[198:201], v[182:185], v[76:79]
	v_mfma_f32_16x16x32_bf16 v[72:75], v[210:213], v[182:185], v[72:75]
	v_mfma_f32_16x16x32_bf16 v[68:71], v[198:201], v[190:193], v[68:71]
	v_mfma_f32_16x16x32_bf16 v[64:67], v[210:213], v[190:193], v[64:67]
	v_mfma_f32_16x16x32_bf16 v[108:111], v[202:205], v[170:173], v[108:111]
	v_mfma_f32_16x16x32_bf16 v[104:107], v[214:217], v[170:173], v[104:107]
	v_mfma_f32_16x16x32_bf16 v[92:95], v[202:205], v[178:181], v[92:95]
	v_mfma_f32_16x16x32_bf16 v[88:91], v[214:217], v[178:181], v[88:91]
	v_mfma_f32_16x16x32_bf16 v[76:79], v[202:205], v[186:189], v[76:79]
	v_mfma_f32_16x16x32_bf16 v[72:75], v[214:217], v[186:189], v[72:75]
	v_mfma_f32_16x16x32_bf16 v[68:71], v[202:205], v[194:197], v[68:71]
	v_mfma_f32_16x16x32_bf16 v[64:67], v[214:217], v[194:197], v[64:67]
	s_setprio 0
	s_mov_b32 m0, s24
	v_lshl_add_u64 v[220:221], s[20:21], 0, v[128:129]
	s_barrier
	ds_read_b128 v[166:169], v148 offset:16384
	ds_read_b128 v[170:173], v148 offset:17408
	ds_read_b128 v[174:177], v148 offset:18432
	ds_read_b128 v[178:181], v148 offset:19456
	ds_read_b128 v[182:185], v148 offset:20480
	ds_read_b128 v[186:189], v148 offset:21504
	ds_read_b128 v[190:193], v148 offset:22528
	ds_read_b128 v[194:197], v148 offset:23552
	global_load_lds_dwordx4 v[220:221], off
	v_lshl_add_u64 v[222:223], s[20:21], 0, v[132:133]
	s_mov_b32 m0, s25
	s_nop 0
	global_load_lds_dwordx4 v[222:223], off
	s_waitcnt vmcnt(10)
	s_barrier
	s_waitcnt lgkmcnt(0)
	s_setprio 1
	s_waitcnt lgkmcnt(0)
	v_mfma_f32_16x16x32_bf16 v[60:63], v[150:153], v[166:169], v[60:63]
	v_mfma_f32_16x16x32_bf16 v[56:59], v[158:161], v[166:169], v[56:59]
	v_mfma_f32_16x16x32_bf16 v[52:55], v[150:153], v[174:177], v[52:55]
	v_mfma_f32_16x16x32_bf16 v[48:51], v[158:161], v[174:177], v[48:51]
	v_mfma_f32_16x16x32_bf16 v[36:39], v[150:153], v[182:185], v[36:39]
	v_mfma_f32_16x16x32_bf16 v[32:35], v[158:161], v[182:185], v[32:35]
	v_mfma_f32_16x16x32_bf16 v[20:23], v[150:153], v[190:193], v[20:23]
	v_mfma_f32_16x16x32_bf16 v[16:19], v[158:161], v[190:193], v[16:19]
	v_mfma_f32_16x16x32_bf16 v[60:63], v[154:157], v[170:173], v[60:63]
	v_mfma_f32_16x16x32_bf16 v[56:59], v[162:165], v[170:173], v[56:59]
	v_mfma_f32_16x16x32_bf16 v[52:55], v[154:157], v[178:181], v[52:55]
	v_mfma_f32_16x16x32_bf16 v[48:51], v[162:165], v[178:181], v[48:51]
	v_mfma_f32_16x16x32_bf16 v[36:39], v[154:157], v[186:189], v[36:39]
	v_mfma_f32_16x16x32_bf16 v[32:35], v[162:165], v[186:189], v[32:35]
	v_mfma_f32_16x16x32_bf16 v[20:23], v[154:157], v[194:197], v[20:23]
	v_mfma_f32_16x16x32_bf16 v[16:19], v[162:165], v[194:197], v[16:19]
	s_setprio 0
	s_barrier
	s_add_u32 s14, s18, 0xe0000
	s_addc_u32 s15, s19, 0
	s_add_i32 s45, s36, s23
	v_lshl_add_u64 v[150:151], s[14:15], 0, v[130:131]
	s_mov_b32 m0, s45
	s_nop 0
	global_load_lds_dwordx4 v[150:151], off
	v_lshl_add_u64 v[150:151], s[14:15], 0, v[134:135]
	s_add_i32 m0, s45, 0x2000
	s_nop 0
	global_load_lds_dwordx4 v[150:151], off
	s_add_i32 s45, 0, 0x18000
	v_add_u32_e32 v162, s45, v146
	ds_read_b128 v[150:153], v162
	ds_read_b128 v[154:157], v162 offset:1024
	ds_read_b128 v[158:161], v162 offset:2048
	ds_read_b128 v[162:165], v162 offset:3072
	s_waitcnt vmcnt(6)
	s_barrier
	s_setprio 1
	v_mfma_f32_16x16x32_bf16 v[44:47], v[198:201], v[166:169], v[44:47]
	v_mfma_f32_16x16x32_bf16 v[40:43], v[210:213], v[166:169], v[40:43]
	v_mfma_f32_16x16x32_bf16 v[28:31], v[198:201], v[174:177], v[28:31]
	v_mfma_f32_16x16x32_bf16 v[24:27], v[210:213], v[174:177], v[24:27]
	v_mfma_f32_16x16x32_bf16 v[12:15], v[198:201], v[182:185], v[12:15]
	v_mfma_f32_16x16x32_bf16 v[8:11], v[210:213], v[182:185], v[8:11]
	v_mfma_f32_16x16x32_bf16 v[4:7], v[198:201], v[190:193], v[4:7]
	v_mfma_f32_16x16x32_bf16 v[0:3], v[210:213], v[190:193], v[0:3]
	v_mfma_f32_16x16x32_bf16 v[44:47], v[202:205], v[170:173], v[44:47]
	v_mfma_f32_16x16x32_bf16 v[40:43], v[214:217], v[170:173], v[40:43]
	v_mfma_f32_16x16x32_bf16 v[28:31], v[202:205], v[178:181], v[28:31]
	v_mfma_f32_16x16x32_bf16 v[24:27], v[214:217], v[178:181], v[24:27]
	v_mfma_f32_16x16x32_bf16 v[12:15], v[202:205], v[186:189], v[12:15]
	v_mfma_f32_16x16x32_bf16 v[8:11], v[214:217], v[186:189], v[8:11]
	v_mfma_f32_16x16x32_bf16 v[4:7], v[202:205], v[194:197], v[4:7]
	v_mfma_f32_16x16x32_bf16 v[0:3], v[214:217], v[194:197], v[0:3]
	s_setprio 0
	s_barrier
	s_add_u32 s14, s20, 0xe0000
	s_addc_u32 s15, s21, 0
	s_mov_b32 m0, s26
	v_lshl_add_u64 v[198:199], s[14:15], 0, v[128:129]
	ds_read_b128 v[166:169], v148 offset:32768
	ds_read_b128 v[170:173], v148 offset:33792
	ds_read_b128 v[174:177], v148 offset:34816
	ds_read_b128 v[178:181], v148 offset:35840
	ds_read_b128 v[182:185], v148 offset:36864
	ds_read_b128 v[186:189], v148 offset:37888
	ds_read_b128 v[190:193], v148 offset:38912
	ds_read_b128 v[194:197], v148 offset:39936
	global_load_lds_dwordx4 v[198:199], off
	v_lshl_add_u64 v[198:199], s[14:15], 0, v[132:133]
	s_mov_b32 m0, s27
	s_nop 0
	global_load_lds_dwordx4 v[198:199], off
	s_waitcnt lgkmcnt(8)
	s_barrier
	s_waitcnt lgkmcnt(0)
	s_setprio 1
	s_waitcnt lgkmcnt(0)
	v_mfma_f32_16x16x32_bf16 v[124:127], v[150:153], v[166:169], v[124:127]
	v_mfma_f32_16x16x32_bf16 v[120:123], v[158:161], v[166:169], v[120:123]
	v_mfma_f32_16x16x32_bf16 v[116:119], v[150:153], v[174:177], v[116:119]
	v_mfma_f32_16x16x32_bf16 v[112:115], v[158:161], v[174:177], v[112:115]
	v_mfma_f32_16x16x32_bf16 v[100:103], v[150:153], v[182:185], v[100:103]
	v_mfma_f32_16x16x32_bf16 v[96:99], v[158:161], v[182:185], v[96:99]
	v_mfma_f32_16x16x32_bf16 v[84:87], v[150:153], v[190:193], v[84:87]
	v_mfma_f32_16x16x32_bf16 v[80:83], v[158:161], v[190:193], v[80:83]
	v_mfma_f32_16x16x32_bf16 v[124:127], v[154:157], v[170:173], v[124:127]
	v_mfma_f32_16x16x32_bf16 v[120:123], v[162:165], v[170:173], v[120:123]
	v_mfma_f32_16x16x32_bf16 v[116:119], v[154:157], v[178:181], v[116:119]
	v_mfma_f32_16x16x32_bf16 v[112:115], v[162:165], v[178:181], v[112:115]
	v_mfma_f32_16x16x32_bf16 v[100:103], v[154:157], v[186:189], v[100:103]
	v_mfma_f32_16x16x32_bf16 v[96:99], v[162:165], v[186:189], v[96:99]
	v_mfma_f32_16x16x32_bf16 v[84:87], v[154:157], v[194:197], v[84:87]
	v_mfma_f32_16x16x32_bf16 v[80:83], v[162:165], v[194:197], v[80:83]
	s_setprio 0
	s_barrier
	s_add_i32 s20, 0, 0x1c000
	s_add_i32 s14, s45, s23
	v_add_u32_e32 v214, s20, v146
	v_lshl_add_u64 v[206:207], v[206:207], 0, s[8:9]
	s_mov_b32 m0, s14
	ds_read_b128 v[198:201], v214
	ds_read_b128 v[202:205], v214 offset:1024
	ds_read_b128 v[210:213], v214 offset:2048
	ds_read_b128 v[214:217], v214 offset:3072
	global_load_lds_dwordx4 v[206:207], off
	v_lshl_add_u64 v[206:207], v[218:219], 0, s[8:9]
	s_add_i32 m0, s14, 0x2000
	s_nop 0
	global_load_lds_dwordx4 v[206:207], off
	s_barrier
	s_waitcnt lgkmcnt(0)
	s_setprio 1
	s_waitcnt lgkmcnt(0)
	v_mfma_f32_16x16x32_bf16 v[108:111], v[198:201], v[166:169], v[108:111]
	v_mfma_f32_16x16x32_bf16 v[104:107], v[210:213], v[166:169], v[104:107]
	v_mfma_f32_16x16x32_bf16 v[92:95], v[198:201], v[174:177], v[92:95]
	v_mfma_f32_16x16x32_bf16 v[88:91], v[210:213], v[174:177], v[88:91]
	v_mfma_f32_16x16x32_bf16 v[76:79], v[198:201], v[182:185], v[76:79]
	v_mfma_f32_16x16x32_bf16 v[72:75], v[210:213], v[182:185], v[72:75]
	v_mfma_f32_16x16x32_bf16 v[68:71], v[198:201], v[190:193], v[68:71]
	v_mfma_f32_16x16x32_bf16 v[64:67], v[210:213], v[190:193], v[64:67]
	v_mfma_f32_16x16x32_bf16 v[108:111], v[202:205], v[170:173], v[108:111]
	v_mfma_f32_16x16x32_bf16 v[104:107], v[214:217], v[170:173], v[104:107]
	v_mfma_f32_16x16x32_bf16 v[92:95], v[202:205], v[178:181], v[92:95]
	v_mfma_f32_16x16x32_bf16 v[88:91], v[214:217], v[178:181], v[88:91]
	v_mfma_f32_16x16x32_bf16 v[76:79], v[202:205], v[186:189], v[76:79]
	v_mfma_f32_16x16x32_bf16 v[72:75], v[214:217], v[186:189], v[72:75]
	v_mfma_f32_16x16x32_bf16 v[68:71], v[202:205], v[194:197], v[68:71]
	v_mfma_f32_16x16x32_bf16 v[64:67], v[214:217], v[194:197], v[64:67]
	s_setprio 0
	s_mov_b32 m0, s31
	v_lshl_add_u64 v[206:207], v[220:221], 0, s[8:9]
	s_barrier
	ds_read_b128 v[166:169], v148 offset:49152
	ds_read_b128 v[170:173], v148 offset:50176
	ds_read_b128 v[174:177], v148 offset:51200
	ds_read_b128 v[178:181], v148 offset:52224
	ds_read_b128 v[182:185], v148 offset:53248
	ds_read_b128 v[186:189], v148 offset:54272
	ds_read_b128 v[190:193], v148 offset:55296
	ds_read_b128 v[194:197], v148 offset:56320
	global_load_lds_dwordx4 v[206:207], off
	v_lshl_add_u64 v[206:207], v[222:223], 0, s[8:9]
	s_mov_b32 m0, s33
	s_nop 0
	global_load_lds_dwordx4 v[206:207], off
	s_waitcnt vmcnt(10)
	s_barrier
	s_waitcnt lgkmcnt(0)
	s_setprio 1
	s_waitcnt lgkmcnt(0)
	v_mfma_f32_16x16x32_bf16 v[60:63], v[150:153], v[166:169], v[60:63]
	v_mfma_f32_16x16x32_bf16 v[56:59], v[158:161], v[166:169], v[56:59]
	v_mfma_f32_16x16x32_bf16 v[52:55], v[150:153], v[174:177], v[52:55]
	v_mfma_f32_16x16x32_bf16 v[48:51], v[158:161], v[174:177], v[48:51]
	v_mfma_f32_16x16x32_bf16 v[36:39], v[150:153], v[182:185], v[36:39]
	v_mfma_f32_16x16x32_bf16 v[32:35], v[158:161], v[182:185], v[32:35]
	v_mfma_f32_16x16x32_bf16 v[20:23], v[150:153], v[190:193], v[20:23]
	v_mfma_f32_16x16x32_bf16 v[16:19], v[158:161], v[190:193], v[16:19]
	v_mfma_f32_16x16x32_bf16 v[60:63], v[154:157], v[170:173], v[60:63]
	v_mfma_f32_16x16x32_bf16 v[56:59], v[162:165], v[170:173], v[56:59]
	v_mfma_f32_16x16x32_bf16 v[52:55], v[154:157], v[178:181], v[52:55]
	v_mfma_f32_16x16x32_bf16 v[48:51], v[162:165], v[178:181], v[48:51]
	v_mfma_f32_16x16x32_bf16 v[36:39], v[154:157], v[186:189], v[36:39]
	v_mfma_f32_16x16x32_bf16 v[32:35], v[162:165], v[186:189], v[32:35]
	v_mfma_f32_16x16x32_bf16 v[20:23], v[154:157], v[194:197], v[20:23]
	v_mfma_f32_16x16x32_bf16 v[16:19], v[162:165], v[194:197], v[16:19]
	s_setprio 0
	s_barrier
	s_add_u32 s14, s18, 0xe0080
	s_addc_u32 s15, s19, 0
	s_add_i32 s18, s20, s23
	v_lshl_add_u64 v[150:151], s[14:15], 0, v[130:131]
	s_mov_b32 m0, s18
	s_nop 0
	global_load_lds_dwordx4 v[150:151], off
	v_lshl_add_u64 v[150:151], s[14:15], 0, v[134:135]
	s_add_i32 m0, s18, 0x2000
	s_nop 0
	global_load_lds_dwordx4 v[150:151], off
	ds_read_b128 v[150:153], v147
	ds_read_b128 v[154:157], v147 offset:1024
	ds_read_b128 v[158:161], v147 offset:2048
	ds_read_b128 v[162:165], v147 offset:3072
	s_waitcnt vmcnt(6)
	s_barrier
	s_setprio 1
	s_waitcnt lgkmcnt(0)
	v_mfma_f32_16x16x32_bf16 v[44:47], v[198:201], v[166:169], v[44:47]
	v_mfma_f32_16x16x32_bf16 v[40:43], v[210:213], v[166:169], v[40:43]
	v_mfma_f32_16x16x32_bf16 v[28:31], v[198:201], v[174:177], v[28:31]
	v_mfma_f32_16x16x32_bf16 v[24:27], v[210:213], v[174:177], v[24:27]
	v_mfma_f32_16x16x32_bf16 v[12:15], v[198:201], v[182:185], v[12:15]
	v_mfma_f32_16x16x32_bf16 v[8:11], v[210:213], v[182:185], v[8:11]
	v_mfma_f32_16x16x32_bf16 v[4:7], v[198:201], v[190:193], v[4:7]
	v_mfma_f32_16x16x32_bf16 v[0:3], v[210:213], v[190:193], v[0:3]
	v_mfma_f32_16x16x32_bf16 v[44:47], v[202:205], v[170:173], v[44:47]
	v_mfma_f32_16x16x32_bf16 v[40:43], v[214:217], v[170:173], v[40:43]
	v_mfma_f32_16x16x32_bf16 v[28:31], v[202:205], v[178:181], v[28:31]
	v_mfma_f32_16x16x32_bf16 v[24:27], v[214:217], v[178:181], v[24:27]
	v_mfma_f32_16x16x32_bf16 v[12:15], v[202:205], v[186:189], v[12:15]
	v_mfma_f32_16x16x32_bf16 v[8:11], v[214:217], v[186:189], v[8:11]
	v_mfma_f32_16x16x32_bf16 v[4:7], v[202:205], v[194:197], v[4:7]
	v_mfma_f32_16x16x32_bf16 v[0:3], v[214:217], v[194:197], v[0:3]
	s_setprio 0
	s_add_i32 s44, s44, 2
	s_add_u32 s42, s42, 0x100
	s_addc_u32 s43, s43, 0
	s_cmp_gt_u32 s44, 53
	s_mov_b64 s[14:15], s[16:17]
	s_barrier
	s_cbranch_scc0 .LBB0_974
	v_mov_b32_e32 v150, v145
	v_mov_b32_e32 v151, v144
	s_lshl_b32 s14, s34, 8
	s_add_i32 s14, s14, s29
	v_add_u32_e32 v150, s14, v150
	s_lshl_b32 s14, s41, 8
	s_or_b32 s14, s14, s30
	v_lshl_add_u32 v152, v151, 3, s14
	v_ashrrev_i32_e32 v151, 31, v150
	v_lshlrev_b64 v[150:151], 12, v[150:151]
	v_ashrrev_i32_e32 v153, 31, v152
	v_lshl_add_u64 v[150:151], s[10:11], 0, v[150:151]
	v_lshl_add_u64 v[150:151], v[152:153], 1, v[150:151]
	v_cvt_pk_bf16_f32 v108, v108, v109
	v_cvt_pk_bf16_f32 v109, v110, v111
	v_cvt_pk_bf16_f32 v110, v104, v105
	v_cvt_pk_bf16_f32 v111, v106, v107
	s_mov_b64 s[14:15], 0x10000
	global_store_dwordx4 v[150:151], v[108:111], off offset:256
	v_cvt_pk_bf16_f32 v92, v92, v93
	v_cvt_pk_bf16_f32 v93, v94, v95
	v_lshl_add_u64 v[108:109], v[150:151], 0, s[14:15]
	s_mov_b32 s14, 0x10000
	v_add_co_u32_e32 v110, vcc, s14, v150
	v_cvt_pk_bf16_f32 v94, v88, v89
	v_cvt_pk_bf16_f32 v95, v90, v91
	s_mov_b64 s[14:15], 0x20000
	v_addc_co_u32_e32 v111, vcc, 0, v151, vcc
	global_store_dwordx4 v[108:109], v[92:95], off offset:256
	v_cvt_pk_bf16_f32 v76, v76, v77
	v_cvt_pk_bf16_f32 v77, v78, v79
	v_lshl_add_u64 v[92:93], v[150:151], 0, s[14:15]
	s_mov_b32 s14, 0x20000
	v_add_co_u32_e32 v94, vcc, s14, v150
	v_cvt_pk_bf16_f32 v78, v72, v73
	v_cvt_pk_bf16_f32 v79, v74, v75
	s_mov_b64 s[14:15], 0x30000
	v_addc_co_u32_e32 v95, vcc, 0, v151, vcc
	global_store_dwordx4 v[92:93], v[76:79], off offset:256
	v_cvt_pk_bf16_f32 v68, v68, v69
	v_cvt_pk_bf16_f32 v69, v70, v71
	v_lshl_add_u64 v[76:77], v[150:151], 0, s[14:15]
	s_mov_b32 s14, 0x30000
	v_add_co_u32_e32 v78, vcc, s14, v150
	s_mov_b64 s[14:15], 0x80000
	s_nop 0
	v_addc_co_u32_e32 v79, vcc, 0, v151, vcc
	v_cvt_pk_bf16_f32 v70, v64, v65
	v_lshl_add_u64 v[64:65], v[150:151], 0, s[14:15]
	s_mov_b32 s14, 0x80000
	v_cvt_pk_bf16_f32 v60, v60, v61
	v_cvt_pk_bf16_f32 v61, v62, v63
	v_cvt_pk_bf16_f32 v62, v56, v57
	v_add_co_u32_e32 v56, vcc, s14, v150
	v_cvt_pk_bf16_f32 v44, v44, v45
	v_cvt_pk_bf16_f32 v45, v46, v47
	v_cvt_pk_bf16_f32 v46, v40, v41
	v_cvt_pk_bf16_f32 v47, v42, v43
	s_mov_b64 s[14:15], 0x90000
	v_addc_co_u32_e32 v57, vcc, 0, v151, vcc
	global_store_dwordx4 v[64:65], v[44:47], off offset:256
	v_cvt_pk_bf16_f32 v28, v28, v29
	v_cvt_pk_bf16_f32 v29, v30, v31
	v_lshl_add_u64 v[44:45], v[150:151], 0, s[14:15]
	s_mov_b32 s14, 0x90000
	v_add_co_u32_e32 v46, vcc, s14, v150
	v_cvt_pk_bf16_f32 v30, v24, v25
	s_nop 0
	v_addc_co_u32_e32 v47, vcc, 0, v151, vcc
	v_cvt_pk_bf16_f32 v31, v26, v27
	global_store_dwordx4 v[44:45], v[28:31], off offset:256
	s_mov_b64 s[14:15], 0xa0000
	v_cvt_pk_bf16_f32 v12, v12, v13
	v_add_co_u32_e32 v30, vcc, s37, v150
	v_lshl_add_u64 v[28:29], v[150:151], 0, s[14:15]
	s_nop 0
	v_addc_co_u32_e32 v31, vcc, 0, v151, vcc
	v_cvt_pk_bf16_f32 v13, v14, v15
	v_cvt_pk_bf16_f32 v14, v8, v9
	v_cvt_pk_bf16_f32 v15, v10, v11
	global_store_dwordx4 v[28:29], v[12:15], off offset:256
	v_cvt_pk_bf16_f32 v124, v124, v125
	v_cvt_pk_bf16_f32 v125, v126, v127
	v_add_co_u32_e32 v14, vcc, s38, v150
	v_cvt_pk_bf16_f32 v126, v120, v121
	s_nop 0
	v_addc_co_u32_e32 v15, vcc, 0, v151, vcc
	v_cvt_pk_bf16_f32 v127, v122, v123
	v_cvt_pk_bf16_f32 v104, v116, v117
	v_cvt_pk_bf16_f32 v105, v118, v119
	v_cvt_pk_bf16_f32 v106, v112, v113
	v_cvt_pk_bf16_f32 v107, v114, v115
	v_cvt_pk_bf16_f32 v88, v100, v101
	v_cvt_pk_bf16_f32 v89, v102, v103
	v_cvt_pk_bf16_f32 v90, v96, v97
	v_cvt_pk_bf16_f32 v91, v98, v99
	v_cvt_pk_bf16_f32 v72, v84, v85
	v_cvt_pk_bf16_f32 v73, v86, v87
	v_cvt_pk_bf16_f32 v74, v80, v81
	v_cvt_pk_bf16_f32 v75, v82, v83
	v_cvt_pk_bf16_f32 v71, v66, v67
	v_cvt_pk_bf16_f32 v63, v58, v59
	v_cvt_pk_bf16_f32 v40, v52, v53
	v_cvt_pk_bf16_f32 v41, v54, v55
	v_cvt_pk_bf16_f32 v42, v48, v49
	v_cvt_pk_bf16_f32 v43, v50, v51
	v_cvt_pk_bf16_f32 v24, v36, v37
	v_cvt_pk_bf16_f32 v25, v38, v39
	v_cvt_pk_bf16_f32 v26, v32, v33
	v_cvt_pk_bf16_f32 v27, v34, v35
	v_lshl_add_u64 v[12:13], v[150:151], 0, s[12:13]
	v_cvt_pk_bf16_f32 v8, v20, v21
	v_cvt_pk_bf16_f32 v9, v22, v23
	v_cvt_pk_bf16_f32 v10, v16, v17
	v_cvt_pk_bf16_f32 v11, v18, v19
	v_cvt_pk_bf16_f32 v4, v4, v5
	v_cvt_pk_bf16_f32 v5, v6, v7
	v_cvt_pk_bf16_f32 v6, v0, v1
	v_cvt_pk_bf16_f32 v7, v2, v3
	s_and_b64 vcc, exec, s[0:1]
	s_mov_b32 s41, s39
	s_mov_b32 s34, s40
	s_mov_b64 s[16:17], s[4:5]
	s_mov_b64 s[14:15], s[2:3]
	global_store_dwordx4 v[150:151], v[124:127], off
	global_store_dwordx4 v[110:111], v[104:107], off
	global_store_dwordx4 v[94:95], v[88:91], off
	global_store_dwordx4 v[78:79], v[72:75], off
	global_store_dwordx4 v[76:77], v[68:71], off offset:256
	global_store_dwordx4 v[56:57], v[60:63], off
	global_store_dwordx4 v[46:47], v[40:43], off
	global_store_dwordx4 v[30:31], v[24:27], off
	global_store_dwordx4 v[14:15], v[8:11], off
	global_store_dwordx4 v[12:13], v[4:7], off offset:256
	s_cbranch_vccz .LBB0_963
	s_waitcnt vmcnt(0)
	s_cmpk_gt_u32 s22, 0xff
	s_cbranch_scc1 .LBB0_978
	s_barrier

.LBB0_1199:
	s_ashr_i32 s23, s22, 31
	v_cmp_lt_i64_e32 vcc, s[24:25], v[140:141]
	s_lshl_b64 s[24:25], s[22:23], 20
	s_add_u32 s24, s36, s24
	s_addc_u32 s25, s37, s25
	s_and_b64 s[26:27], vcc, exec
	s_cselect_b32 s4, s25, s29
	s_cselect_b32 s7, s24, s28
	s_ashr_i32 s21, s20, 31
	s_lshl_b64 s[26:27], s[20:21], 20
	s_add_u32 s26, s66, s26
	s_addc_u32 s27, s67, s27
	s_and_b64 s[34:35], vcc, exec
	s_cselect_b32 s21, s27, s31
	s_cselect_b32 s23, s26, s30
	s_add_u32 s28, s28, 0x80080
	s_addc_u32 s29, s29, 0
	s_add_u32 s54, s30, 0x100
	v_mov_b32_e32 v0, 0
	s_addc_u32 s55, s31, 0
	s_mov_b32 s56, -2
	v_mov_b32_e32 v1, v0
	v_mov_b32_e32 v2, v0
	v_mov_b32_e32 v3, v0
	v_mov_b32_e32 v4, v0
	v_mov_b32_e32 v5, v0
	v_mov_b32_e32 v6, v0
	v_mov_b32_e32 v7, v0
	v_mov_b32_e32 v8, v0
	v_mov_b32_e32 v9, v0
	v_mov_b32_e32 v10, v0
	v_mov_b32_e32 v11, v0
	v_mov_b32_e32 v12, v0
	v_mov_b32_e32 v13, v0
	v_mov_b32_e32 v14, v0
	v_mov_b32_e32 v15, v0
	v_mov_b32_e32 v24, v0
	v_mov_b32_e32 v25, v0
	v_mov_b32_e32 v26, v0
	v_mov_b32_e32 v27, v0
	v_mov_b32_e32 v28, v0
	v_mov_b32_e32 v29, v0
	v_mov_b32_e32 v30, v0
	v_mov_b32_e32 v31, v0
	v_mov_b32_e32 v40, v0
	v_mov_b32_e32 v41, v0
	v_mov_b32_e32 v42, v0
	v_mov_b32_e32 v43, v0
	v_mov_b32_e32 v44, v0
	v_mov_b32_e32 v45, v0
	v_mov_b32_e32 v46, v0
	v_mov_b32_e32 v47, v0
	v_mov_b32_e32 v16, v0
	v_mov_b32_e32 v17, v0
	v_mov_b32_e32 v18, v0
	v_mov_b32_e32 v19, v0
	v_mov_b32_e32 v20, v0
	v_mov_b32_e32 v21, v0
	v_mov_b32_e32 v22, v0
	v_mov_b32_e32 v23, v0
	v_mov_b32_e32 v32, v0
	v_mov_b32_e32 v33, v0
	v_mov_b32_e32 v34, v0
	v_mov_b32_e32 v35, v0
	v_mov_b32_e32 v36, v0
	v_mov_b32_e32 v37, v0
	v_mov_b32_e32 v38, v0
	v_mov_b32_e32 v39, v0
	v_mov_b32_e32 v48, v0
	v_mov_b32_e32 v49, v0
	v_mov_b32_e32 v50, v0
	v_mov_b32_e32 v51, v0
	v_mov_b32_e32 v52, v0
	v_mov_b32_e32 v53, v0
	v_mov_b32_e32 v54, v0
	v_mov_b32_e32 v55, v0
	v_mov_b32_e32 v56, v0
	v_mov_b32_e32 v57, v0
	v_mov_b32_e32 v58, v0
	v_mov_b32_e32 v59, v0
	v_mov_b32_e32 v60, v0
	v_mov_b32_e32 v61, v0
	v_mov_b32_e32 v62, v0
	v_mov_b32_e32 v63, v0
	v_mov_b32_e32 v64, v0
	v_mov_b32_e32 v65, v0
	v_mov_b32_e32 v66, v0
	v_mov_b32_e32 v67, v0
	v_mov_b32_e32 v68, v0
	v_mov_b32_e32 v69, v0
	v_mov_b32_e32 v70, v0
	v_mov_b32_e32 v71, v0
	v_mov_b32_e32 v72, v0
	v_mov_b32_e32 v73, v0
	v_mov_b32_e32 v74, v0
	v_mov_b32_e32 v75, v0
	v_mov_b32_e32 v76, v0
	v_mov_b32_e32 v77, v0
	v_mov_b32_e32 v78, v0
	v_mov_b32_e32 v79, v0
	v_mov_b32_e32 v88, v0
	v_mov_b32_e32 v89, v0
	v_mov_b32_e32 v90, v0
	v_mov_b32_e32 v91, v0
	v_mov_b32_e32 v92, v0
	v_mov_b32_e32 v93, v0
	v_mov_b32_e32 v94, v0
	v_mov_b32_e32 v95, v0
	v_mov_b32_e32 v104, v0
	v_mov_b32_e32 v105, v0
	v_mov_b32_e32 v106, v0
	v_mov_b32_e32 v107, v0
	v_mov_b32_e32 v108, v0
	v_mov_b32_e32 v109, v0
	v_mov_b32_e32 v110, v0
	v_mov_b32_e32 v111, v0
	v_mov_b32_e32 v80, v0
	v_mov_b32_e32 v81, v0
	v_mov_b32_e32 v82, v0
	v_mov_b32_e32 v83, v0
	v_mov_b32_e32 v84, v0
	v_mov_b32_e32 v85, v0
	v_mov_b32_e32 v86, v0
	v_mov_b32_e32 v87, v0
	v_mov_b32_e32 v96, v0
	v_mov_b32_e32 v97, v0
	v_mov_b32_e32 v98, v0
	v_mov_b32_e32 v99, v0
	v_mov_b32_e32 v100, v0
	v_mov_b32_e32 v101, v0
	v_mov_b32_e32 v102, v0
	v_mov_b32_e32 v103, v0
	v_mov_b32_e32 v112, v0
	v_mov_b32_e32 v113, v0
	v_mov_b32_e32 v114, v0
	v_mov_b32_e32 v115, v0
	v_mov_b32_e32 v116, v0
	v_mov_b32_e32 v117, v0
	v_mov_b32_e32 v118, v0
	v_mov_b32_e32 v119, v0
	v_mov_b32_e32 v120, v0
	v_mov_b32_e32 v121, v0
	v_mov_b32_e32 v122, v0
	v_mov_b32_e32 v123, v0
	v_mov_b32_e32 v124, v0
	v_mov_b32_e32 v125, v0
	v_mov_b32_e32 v126, v0
	v_mov_b32_e32 v127, v0
	ds_read_b128 v[144:147], v151
	ds_read_b128 v[156:159], v151 offset:1024
	ds_read_b128 v[160:163], v151 offset:2048
	ds_read_b128 v[164:167], v151 offset:3072
.LBB0_1200:
	s_waitcnt lgkmcnt(0)
	s_add_u32 s30, s28, 0xfff80080
	s_addc_u32 s31, s29, -1
	s_cmp_eq_u32 s56, 28
	s_cselect_b32 s35, s4, s31
	s_cselect_b32 s34, s7, s30
	s_cselect_b32 s31, s21, s55
	s_cselect_b32 s30, s23, s54
	v_lshl_add_u64 v[200:201], s[28:29], 0, v[136:137]
	s_add_i32 m0, s17, 0xc000
	ds_read_b128 v[168:171], v152
	ds_read_b128 v[172:175], v152 offset:1024
	ds_read_b128 v[176:179], v152 offset:2048
	ds_read_b128 v[180:183], v152 offset:3072
	ds_read_b128 v[184:187], v152 offset:4096
	ds_read_b128 v[188:191], v152 offset:5120
	ds_read_b128 v[192:195], v152 offset:6144
	ds_read_b128 v[196:199], v152 offset:7168
	global_load_lds_dwordx4 v[200:201], off
	v_lshl_add_u64 v[200:201], s[28:29], 0, v[138:139]
	s_add_i32 m0, s17, 0xe000
	s_nop 0
	global_load_lds_dwordx4 v[200:201], off
	s_waitcnt lgkmcnt(8)
	s_barrier
	s_waitcnt lgkmcnt(0)
	s_setprio 1
	s_waitcnt lgkmcnt(0)
	v_mfma_f32_16x16x32_bf16 v[124:127], v[144:147], v[168:171], v[124:127]
	v_mfma_f32_16x16x32_bf16 v[120:123], v[160:163], v[168:171], v[120:123]
	v_mfma_f32_16x16x32_bf16 v[116:119], v[144:147], v[176:179], v[116:119]
	v_mfma_f32_16x16x32_bf16 v[112:115], v[160:163], v[176:179], v[112:115]
	v_mfma_f32_16x16x32_bf16 v[100:103], v[144:147], v[184:187], v[100:103]
	v_mfma_f32_16x16x32_bf16 v[96:99], v[160:163], v[184:187], v[96:99]
	v_mfma_f32_16x16x32_bf16 v[84:87], v[144:147], v[192:195], v[84:87]
	v_mfma_f32_16x16x32_bf16 v[80:83], v[160:163], v[192:195], v[80:83]
	v_mfma_f32_16x16x32_bf16 v[124:127], v[156:159], v[172:175], v[124:127]
	v_mfma_f32_16x16x32_bf16 v[120:123], v[164:167], v[172:175], v[120:123]
	v_mfma_f32_16x16x32_bf16 v[116:119], v[156:159], v[180:183], v[116:119]
	v_mfma_f32_16x16x32_bf16 v[112:115], v[164:167], v[180:183], v[112:115]
	v_mfma_f32_16x16x32_bf16 v[100:103], v[156:159], v[188:191], v[100:103]
	v_mfma_f32_16x16x32_bf16 v[96:99], v[164:167], v[188:191], v[96:99]
	v_mfma_f32_16x16x32_bf16 v[84:87], v[156:159], v[196:199], v[84:87]
	v_mfma_f32_16x16x32_bf16 v[80:83], v[164:167], v[196:199], v[80:83]
	s_setprio 0
	s_barrier
	s_add_i32 s57, s45, s33
	v_lshl_add_u64 v[218:219], s[30:31], 0, v[130:131]
	s_mov_b32 m0, s57
	ds_read_b128 v[200:203], v153
	ds_read_b128 v[204:207], v153 offset:1024
	ds_read_b128 v[210:213], v153 offset:2048
	ds_read_b128 v[214:217], v153 offset:3072
	global_load_lds_dwordx4 v[218:219], off
	v_lshl_add_u64 v[220:221], s[30:31], 0, v[134:135]
	s_add_i32 m0, s57, 0x2000
	s_nop 0
	global_load_lds_dwordx4 v[220:221], off
	s_barrier
	s_waitcnt lgkmcnt(0)
	s_setprio 1
	s_waitcnt lgkmcnt(0)
	v_mfma_f32_16x16x32_bf16 v[108:111], v[200:203], v[168:171], v[108:111]
	v_mfma_f32_16x16x32_bf16 v[104:107], v[210:213], v[168:171], v[104:107]
	v_mfma_f32_16x16x32_bf16 v[92:95], v[200:203], v[176:179], v[92:95]
	v_mfma_f32_16x16x32_bf16 v[88:91], v[210:213], v[176:179], v[88:91]
	v_mfma_f32_16x16x32_bf16 v[76:79], v[200:203], v[184:187], v[76:79]
	v_mfma_f32_16x16x32_bf16 v[72:75], v[210:213], v[184:187], v[72:75]
	v_mfma_f32_16x16x32_bf16 v[68:71], v[200:203], v[192:195], v[68:71]
	v_mfma_f32_16x16x32_bf16 v[64:67], v[210:213], v[192:195], v[64:67]
	v_mfma_f32_16x16x32_bf16 v[108:111], v[204:207], v[172:175], v[108:111]
	v_mfma_f32_16x16x32_bf16 v[104:107], v[214:217], v[172:175], v[104:107]
	v_mfma_f32_16x16x32_bf16 v[92:95], v[204:207], v[180:183], v[92:95]
	v_mfma_f32_16x16x32_bf16 v[88:91], v[214:217], v[180:183], v[88:91]
	v_mfma_f32_16x16x32_bf16 v[76:79], v[204:207], v[188:191], v[76:79]
	v_mfma_f32_16x16x32_bf16 v[72:75], v[214:217], v[188:191], v[72:75]
	v_mfma_f32_16x16x32_bf16 v[68:71], v[204:207], v[196:199], v[68:71]
	v_mfma_f32_16x16x32_bf16 v[64:67], v[214:217], v[196:199], v[64:67]
	s_setprio 0
	s_mov_b32 m0, s17
	v_lshl_add_u64 v[222:223], s[34:35], 0, v[128:129]
	s_barrier
	ds_read_b128 v[168:171], v152 offset:16384
	ds_read_b128 v[172:175], v152 offset:17408
	ds_read_b128 v[176:179], v152 offset:18432
	ds_read_b128 v[180:183], v152 offset:19456
	ds_read_b128 v[184:187], v152 offset:20480
	ds_read_b128 v[188:191], v152 offset:21504
	ds_read_b128 v[192:195], v152 offset:22528
	ds_read_b128 v[196:199], v152 offset:23552
	global_load_lds_dwordx4 v[222:223], off
	v_lshl_add_u64 v[224:225], s[34:35], 0, v[132:133]
	s_mov_b32 m0, s38
	s_nop 0
	global_load_lds_dwordx4 v[224:225], off
	s_waitcnt vmcnt(10)
	s_barrier
	s_waitcnt lgkmcnt(0)
	s_setprio 1
	s_waitcnt lgkmcnt(0)
	v_mfma_f32_16x16x32_bf16 v[60:63], v[144:147], v[168:171], v[60:63]
	v_mfma_f32_16x16x32_bf16 v[56:59], v[160:163], v[168:171], v[56:59]
	v_mfma_f32_16x16x32_bf16 v[52:55], v[144:147], v[176:179], v[52:55]
	v_mfma_f32_16x16x32_bf16 v[48:51], v[160:163], v[176:179], v[48:51]
	v_mfma_f32_16x16x32_bf16 v[36:39], v[144:147], v[184:187], v[36:39]
	v_mfma_f32_16x16x32_bf16 v[32:35], v[160:163], v[184:187], v[32:35]
	v_mfma_f32_16x16x32_bf16 v[20:23], v[144:147], v[192:195], v[20:23]
	v_mfma_f32_16x16x32_bf16 v[16:19], v[160:163], v[192:195], v[16:19]
	v_mfma_f32_16x16x32_bf16 v[60:63], v[156:159], v[172:175], v[60:63]
	v_mfma_f32_16x16x32_bf16 v[56:59], v[164:167], v[172:175], v[56:59]
	v_mfma_f32_16x16x32_bf16 v[52:55], v[156:159], v[180:183], v[52:55]
	v_mfma_f32_16x16x32_bf16 v[48:51], v[164:167], v[180:183], v[48:51]
	v_mfma_f32_16x16x32_bf16 v[36:39], v[156:159], v[188:191], v[36:39]
	v_mfma_f32_16x16x32_bf16 v[32:35], v[164:167], v[188:191], v[32:35]
	v_mfma_f32_16x16x32_bf16 v[20:23], v[156:159], v[196:199], v[20:23]
	v_mfma_f32_16x16x32_bf16 v[16:19], v[164:167], v[196:199], v[16:19]
	s_setprio 0
	s_barrier
	s_add_u32 s60, s30, 0x80000
	s_addc_u32 s61, s31, 0
	s_add_i32 s57, s51, s33
	v_lshl_add_u64 v[144:145], s[60:61], 0, v[130:131]
	s_mov_b32 m0, s57
	s_nop 0
	global_load_lds_dwordx4 v[144:145], off
	v_lshl_add_u64 v[144:145], s[60:61], 0, v[134:135]
	s_add_i32 m0, s57, 0x2000
	s_nop 0
	global_load_lds_dwordx4 v[144:145], off
	s_add_i32 s57, 0, 0x18000
	v_add_u32_e32 v155, s57, v150
	ds_read_b128 v[144:147], v155
	ds_read_b128 v[156:159], v155 offset:1024
	ds_read_b128 v[160:163], v155 offset:2048
	ds_read_b128 v[164:167], v155 offset:3072
	s_waitcnt vmcnt(6)
	s_barrier
	s_setprio 1
	v_mfma_f32_16x16x32_bf16 v[44:47], v[200:203], v[168:171], v[44:47]
	v_mfma_f32_16x16x32_bf16 v[40:43], v[210:213], v[168:171], v[40:43]
	v_mfma_f32_16x16x32_bf16 v[28:31], v[200:203], v[176:179], v[28:31]
	v_mfma_f32_16x16x32_bf16 v[24:27], v[210:213], v[176:179], v[24:27]
	v_mfma_f32_16x16x32_bf16 v[12:15], v[200:203], v[184:187], v[12:15]
	v_mfma_f32_16x16x32_bf16 v[8:11], v[210:213], v[184:187], v[8:11]
	v_mfma_f32_16x16x32_bf16 v[4:7], v[200:203], v[192:195], v[4:7]
	v_mfma_f32_16x16x32_bf16 v[0:3], v[210:213], v[192:195], v[0:3]
	v_mfma_f32_16x16x32_bf16 v[44:47], v[204:207], v[172:175], v[44:47]
	v_mfma_f32_16x16x32_bf16 v[40:43], v[214:217], v[172:175], v[40:43]
	v_mfma_f32_16x16x32_bf16 v[28:31], v[204:207], v[180:183], v[28:31]
	v_mfma_f32_16x16x32_bf16 v[24:27], v[214:217], v[180:183], v[24:27]
	v_mfma_f32_16x16x32_bf16 v[12:15], v[204:207], v[188:191], v[12:15]
	v_mfma_f32_16x16x32_bf16 v[8:11], v[214:217], v[188:191], v[8:11]
	v_mfma_f32_16x16x32_bf16 v[4:7], v[204:207], v[196:199], v[4:7]
	v_mfma_f32_16x16x32_bf16 v[0:3], v[214:217], v[196:199], v[0:3]
	s_setprio 0
	s_barrier
	s_add_u32 s34, s34, 0x80000
	s_addc_u32 s35, s35, 0
	s_mov_b32 m0, s39
	v_lshl_add_u64 v[200:201], s[34:35], 0, v[128:129]
	ds_read_b128 v[168:171], v152 offset:32768
	ds_read_b128 v[172:175], v152 offset:33792
	ds_read_b128 v[176:179], v152 offset:34816
	ds_read_b128 v[180:183], v152 offset:35840
	ds_read_b128 v[184:187], v152 offset:36864
	ds_read_b128 v[188:191], v152 offset:37888
	ds_read_b128 v[192:195], v152 offset:38912
	ds_read_b128 v[196:199], v152 offset:39936
	global_load_lds_dwordx4 v[200:201], off
	v_lshl_add_u64 v[200:201], s[34:35], 0, v[132:133]
	s_mov_b32 m0, s40
	s_nop 0
	global_load_lds_dwordx4 v[200:201], off
	s_waitcnt lgkmcnt(8)
	s_barrier
	s_waitcnt lgkmcnt(0)
	s_setprio 1
	s_waitcnt lgkmcnt(0)
	v_mfma_f32_16x16x32_bf16 v[124:127], v[144:147], v[168:171], v[124:127]
	v_mfma_f32_16x16x32_bf16 v[120:123], v[160:163], v[168:171], v[120:123]
	v_mfma_f32_16x16x32_bf16 v[116:119], v[144:147], v[176:179], v[116:119]
	v_mfma_f32_16x16x32_bf16 v[112:115], v[160:163], v[176:179], v[112:115]
	v_mfma_f32_16x16x32_bf16 v[100:103], v[144:147], v[184:187], v[100:103]
	v_mfma_f32_16x16x32_bf16 v[96:99], v[160:163], v[184:187], v[96:99]
	v_mfma_f32_16x16x32_bf16 v[84:87], v[144:147], v[192:195], v[84:87]
	v_mfma_f32_16x16x32_bf16 v[80:83], v[160:163], v[192:195], v[80:83]
	v_mfma_f32_16x16x32_bf16 v[124:127], v[156:159], v[172:175], v[124:127]
	v_mfma_f32_16x16x32_bf16 v[120:123], v[164:167], v[172:175], v[120:123]
	v_mfma_f32_16x16x32_bf16 v[116:119], v[156:159], v[180:183], v[116:119]
	v_mfma_f32_16x16x32_bf16 v[112:115], v[164:167], v[180:183], v[112:115]
	v_mfma_f32_16x16x32_bf16 v[100:103], v[156:159], v[188:191], v[100:103]
	v_mfma_f32_16x16x32_bf16 v[96:99], v[164:167], v[188:191], v[96:99]
	v_mfma_f32_16x16x32_bf16 v[84:87], v[156:159], v[196:199], v[84:87]
	v_mfma_f32_16x16x32_bf16 v[80:83], v[164:167], v[196:199], v[80:83]
	s_setprio 0
	s_barrier
	s_add_i32 s34, 0, 0x1c000
	s_add_i32 s35, s57, s33
	v_add_u32_e32 v155, s34, v150
	v_lshl_add_u64 v[218:219], v[218:219], 0, s[8:9]
	s_mov_b32 m0, s35
	ds_read_b128 v[200:203], v155
	ds_read_b128 v[204:207], v155 offset:1024
	ds_read_b128 v[210:213], v155 offset:2048
	ds_read_b128 v[214:217], v155 offset:3072
	global_load_lds_dwordx4 v[218:219], off
	v_lshl_add_u64 v[218:219], v[220:221], 0, s[8:9]
	s_add_i32 m0, s35, 0x2000
	s_nop 0
	global_load_lds_dwordx4 v[218:219], off
	s_barrier
	s_waitcnt lgkmcnt(0)
	s_setprio 1
	s_waitcnt lgkmcnt(0)
	v_mfma_f32_16x16x32_bf16 v[108:111], v[200:203], v[168:171], v[108:111]
	v_mfma_f32_16x16x32_bf16 v[104:107], v[210:213], v[168:171], v[104:107]
	v_mfma_f32_16x16x32_bf16 v[92:95], v[200:203], v[176:179], v[92:95]
	v_mfma_f32_16x16x32_bf16 v[88:91], v[210:213], v[176:179], v[88:91]
	v_mfma_f32_16x16x32_bf16 v[76:79], v[200:203], v[184:187], v[76:79]
	v_mfma_f32_16x16x32_bf16 v[72:75], v[210:213], v[184:187], v[72:75]
	v_mfma_f32_16x16x32_bf16 v[68:71], v[200:203], v[192:195], v[68:71]
	v_mfma_f32_16x16x32_bf16 v[64:67], v[210:213], v[192:195], v[64:67]
	v_mfma_f32_16x16x32_bf16 v[108:111], v[204:207], v[172:175], v[108:111]
	v_mfma_f32_16x16x32_bf16 v[104:107], v[214:217], v[172:175], v[104:107]
	v_mfma_f32_16x16x32_bf16 v[92:95], v[204:207], v[180:183], v[92:95]
	v_mfma_f32_16x16x32_bf16 v[88:91], v[214:217], v[180:183], v[88:91]
	v_mfma_f32_16x16x32_bf16 v[76:79], v[204:207], v[188:191], v[76:79]
	v_mfma_f32_16x16x32_bf16 v[72:75], v[214:217], v[188:191], v[72:75]
	v_mfma_f32_16x16x32_bf16 v[68:71], v[204:207], v[196:199], v[68:71]
	v_mfma_f32_16x16x32_bf16 v[64:67], v[214:217], v[196:199], v[64:67]
	s_setprio 0
	s_mov_b32 m0, s43
	v_lshl_add_u64 v[218:219], v[222:223], 0, s[8:9]
	s_barrier
	ds_read_b128 v[168:171], v152 offset:49152
	ds_read_b128 v[172:175], v152 offset:50176
	ds_read_b128 v[176:179], v152 offset:51200
	ds_read_b128 v[180:183], v152 offset:52224
	ds_read_b128 v[184:187], v152 offset:53248
	ds_read_b128 v[188:191], v152 offset:54272
	ds_read_b128 v[192:195], v152 offset:55296
	ds_read_b128 v[196:199], v152 offset:56320
	global_load_lds_dwordx4 v[218:219], off
	v_lshl_add_u64 v[218:219], v[224:225], 0, s[8:9]
	s_mov_b32 m0, s44
	s_nop 0
	global_load_lds_dwordx4 v[218:219], off
	s_waitcnt vmcnt(10)
	s_barrier
	s_waitcnt lgkmcnt(0)
	s_setprio 1
	s_waitcnt lgkmcnt(0)
	v_mfma_f32_16x16x32_bf16 v[60:63], v[144:147], v[168:171], v[60:63]
	v_mfma_f32_16x16x32_bf16 v[56:59], v[160:163], v[168:171], v[56:59]
	v_mfma_f32_16x16x32_bf16 v[52:55], v[144:147], v[176:179], v[52:55]
	v_mfma_f32_16x16x32_bf16 v[48:51], v[160:163], v[176:179], v[48:51]
	v_mfma_f32_16x16x32_bf16 v[36:39], v[144:147], v[184:187], v[36:39]
	v_mfma_f32_16x16x32_bf16 v[32:35], v[160:163], v[184:187], v[32:35]
	v_mfma_f32_16x16x32_bf16 v[20:23], v[144:147], v[192:195], v[20:23]
	v_mfma_f32_16x16x32_bf16 v[16:19], v[160:163], v[192:195], v[16:19]
	v_mfma_f32_16x16x32_bf16 v[60:63], v[156:159], v[172:175], v[60:63]
	v_mfma_f32_16x16x32_bf16 v[56:59], v[164:167], v[172:175], v[56:59]
	v_mfma_f32_16x16x32_bf16 v[52:55], v[156:159], v[180:183], v[52:55]
	v_mfma_f32_16x16x32_bf16 v[48:51], v[164:167], v[180:183], v[48:51]
	v_mfma_f32_16x16x32_bf16 v[36:39], v[156:159], v[188:191], v[36:39]
	v_mfma_f32_16x16x32_bf16 v[32:35], v[164:167], v[188:191], v[32:35]
	v_mfma_f32_16x16x32_bf16 v[20:23], v[156:159], v[196:199], v[20:23]
	v_mfma_f32_16x16x32_bf16 v[16:19], v[164:167], v[196:199], v[16:19]
	s_setprio 0
	s_barrier
	s_add_u32 s30, s30, 0x80080
	s_addc_u32 s31, s31, 0
	s_add_i32 s34, s34, s33
	v_lshl_add_u64 v[144:145], s[30:31], 0, v[130:131]
	s_mov_b32 m0, s34
	s_nop 0
	global_load_lds_dwordx4 v[144:145], off
	v_lshl_add_u64 v[144:145], s[30:31], 0, v[134:135]
	s_add_i32 m0, s34, 0x2000
	s_nop 0
	global_load_lds_dwordx4 v[144:145], off
	ds_read_b128 v[144:147], v151
	ds_read_b128 v[156:159], v151 offset:1024
	ds_read_b128 v[160:163], v151 offset:2048
	ds_read_b128 v[164:167], v151 offset:3072
	s_waitcnt vmcnt(6)
	s_barrier
	s_setprio 1
	s_waitcnt lgkmcnt(0)
	v_mfma_f32_16x16x32_bf16 v[44:47], v[200:203], v[168:171], v[44:47]
	v_mfma_f32_16x16x32_bf16 v[40:43], v[210:213], v[168:171], v[40:43]
	v_mfma_f32_16x16x32_bf16 v[28:31], v[200:203], v[176:179], v[28:31]
	v_mfma_f32_16x16x32_bf16 v[24:27], v[210:213], v[176:179], v[24:27]
	v_mfma_f32_16x16x32_bf16 v[12:15], v[200:203], v[184:187], v[12:15]
	v_mfma_f32_16x16x32_bf16 v[8:11], v[210:213], v[184:187], v[8:11]
	v_mfma_f32_16x16x32_bf16 v[4:7], v[200:203], v[192:195], v[4:7]
	v_mfma_f32_16x16x32_bf16 v[0:3], v[210:213], v[192:195], v[0:3]
	v_mfma_f32_16x16x32_bf16 v[44:47], v[204:207], v[172:175], v[44:47]
	v_mfma_f32_16x16x32_bf16 v[40:43], v[214:217], v[172:175], v[40:43]
	v_mfma_f32_16x16x32_bf16 v[28:31], v[204:207], v[180:183], v[28:31]
	v_mfma_f32_16x16x32_bf16 v[24:27], v[214:217], v[180:183], v[24:27]
	v_mfma_f32_16x16x32_bf16 v[12:15], v[204:207], v[188:191], v[12:15]
	v_mfma_f32_16x16x32_bf16 v[8:11], v[214:217], v[188:191], v[8:11]
	v_mfma_f32_16x16x32_bf16 v[4:7], v[204:207], v[196:199], v[4:7]
	v_mfma_f32_16x16x32_bf16 v[0:3], v[214:217], v[196:199], v[0:3]
	s_setprio 0
	s_add_i32 s56, s56, 2
	s_add_u32 s28, s28, 0x100
	s_addc_u32 s29, s29, 0
	s_add_u32 s54, s54, 0x100
	s_addc_u32 s55, s55, 0
	s_cmp_gt_u32 s56, 29
	s_barrier
	s_cbranch_scc0 .LBB0_1200
	v_mov_b32_e32 v155, v148
	v_mov_b32_e32 v156, v149
	s_cmp_gt_i32 s6, 7
	s_mov_b64 s[28:29], -1
	s_cbranch_scc0 .LBB0_1231
	s_cmp_gt_u32 s6, 15
	s_cbranch_scc0 .LBB0_1212
	s_cmp_gt_u32 s6, 23
	s_cbranch_scc0 .LBB0_1209
	s_lshl_b32 s4, s16, 8
	s_add_i32 s4, s4, s41
	v_lshl_add_u32 v144, v156, 3, s42
	v_add_u32_e32 v157, s4, v155
	v_ashrrev_i32_e32 v145, 31, v144
	v_mad_i64_i32 v[146:147], s[28:29], v157, s52, 0
	s_cmp_gt_u32 s6, 25
	s_mov_b64 s[28:29], -1
	v_lshl_add_u64 v[146:147], s[14:15], 0, v[146:147]
	v_lshlrev_b64 v[144:145], 1, v[144:145]
	v_add_u32_e32 v163, 16, v157
	v_add_u32_e32 v162, 32, v157
	v_add_u32_e32 v161, 48, v157
	v_add_u32_e32 v160, 0x80, v157
	v_add_u32_e32 v159, 0x90, v157
	v_add_u32_e32 v158, 0xa0, v157
	v_add_u32_e32 v157, 0xb0, v157
	s_cbranch_scc0 .LBB0_1206
	s_lshl_b32 s4, s6, 9
	v_lshl_add_u64 v[168:169], v[146:147], 0, s[4:5]
	v_cvt_pk_bf16_f32 v164, v124, v125
	v_cvt_pk_bf16_f32 v165, v126, v127
	v_cvt_pk_bf16_f32 v166, v120, v121
	v_cvt_pk_bf16_f32 v167, v122, v123
	v_lshl_add_u64 v[168:169], v[168:169], 0, v[144:145]
	global_store_dwordx4 v[168:169], v[164:167], off
	s_nop 1
	v_cvt_pk_bf16_f32 v164, v108, v109
	v_cvt_pk_bf16_f32 v165, v110, v111
	v_cvt_pk_bf16_f32 v166, v104, v105
	v_cvt_pk_bf16_f32 v167, v106, v107
	global_store_dwordx4 v[168:169], v[164:167], off offset:256
	v_mov_b64_e32 v[168:169], s[14:15]
	v_mad_i64_i32 v[170:171], s[28:29], v163, s52, v[168:169]
	v_lshl_add_u64 v[170:171], v[170:171], 0, s[4:5]
	v_cvt_pk_bf16_f32 v164, v116, v117
	v_cvt_pk_bf16_f32 v165, v118, v119
	v_cvt_pk_bf16_f32 v166, v112, v113
	v_cvt_pk_bf16_f32 v167, v114, v115
	v_lshl_add_u64 v[170:171], v[170:171], 0, v[144:145]
	global_store_dwordx4 v[170:171], v[164:167], off
	s_nop 1
	v_cvt_pk_bf16_f32 v164, v92, v93
	v_cvt_pk_bf16_f32 v165, v94, v95
	v_cvt_pk_bf16_f32 v166, v88, v89
	v_cvt_pk_bf16_f32 v167, v90, v91
	global_store_dwordx4 v[170:171], v[164:167], off offset:256
	v_mad_i64_i32 v[170:171], s[28:29], v162, s52, v[168:169]
	v_lshl_add_u64 v[170:171], v[170:171], 0, s[4:5]
	v_cvt_pk_bf16_f32 v164, v100, v101
	v_cvt_pk_bf16_f32 v165, v102, v103
	v_cvt_pk_bf16_f32 v166, v96, v97
	v_cvt_pk_bf16_f32 v167, v98, v99
	v_lshl_add_u64 v[170:171], v[170:171], 0, v[144:145]
	global_store_dwordx4 v[170:171], v[164:167], off
	s_nop 1
	v_cvt_pk_bf16_f32 v164, v76, v77
	v_cvt_pk_bf16_f32 v165, v78, v79
	v_cvt_pk_bf16_f32 v166, v72, v73
	v_cvt_pk_bf16_f32 v167, v74, v75
	global_store_dwordx4 v[170:171], v[164:167], off offset:256
	v_mad_i64_i32 v[170:171], s[28:29], v161, s52, v[168:169]
	v_lshl_add_u64 v[170:171], v[170:171], 0, s[4:5]
	v_cvt_pk_bf16_f32 v164, v84, v85
	v_cvt_pk_bf16_f32 v165, v86, v87
	v_cvt_pk_bf16_f32 v166, v80, v81
	v_cvt_pk_bf16_f32 v167, v82, v83
	v_lshl_add_u64 v[170:171], v[170:171], 0, v[144:145]
	global_store_dwordx4 v[170:171], v[164:167], off
	s_nop 1
	v_cvt_pk_bf16_f32 v164, v68, v69
	v_cvt_pk_bf16_f32 v165, v70, v71
	v_cvt_pk_bf16_f32 v166, v64, v65
	v_cvt_pk_bf16_f32 v167, v66, v67
	global_store_dwordx4 v[170:171], v[164:167], off offset:256
	v_mad_i64_i32 v[170:171], s[28:29], v160, s52, v[168:169]
	v_lshl_add_u64 v[170:171], v[170:171], 0, s[4:5]
	v_cvt_pk_bf16_f32 v164, v60, v61
	v_cvt_pk_bf16_f32 v165, v62, v63
	v_cvt_pk_bf16_f32 v166, v56, v57
	v_cvt_pk_bf16_f32 v167, v58, v59
	v_lshl_add_u64 v[170:171], v[170:171], 0, v[144:145]
	global_store_dwordx4 v[170:171], v[164:167], off
	s_nop 1
	v_cvt_pk_bf16_f32 v164, v44, v45
	v_cvt_pk_bf16_f32 v165, v46, v47
	v_cvt_pk_bf16_f32 v166, v40, v41
	v_cvt_pk_bf16_f32 v167, v42, v43
	global_store_dwordx4 v[170:171], v[164:167], off offset:256
	v_mad_i64_i32 v[170:171], s[28:29], v159, s52, v[168:169]
	v_lshl_add_u64 v[170:171], v[170:171], 0, s[4:5]
	v_cvt_pk_bf16_f32 v164, v52, v53
	v_cvt_pk_bf16_f32 v165, v54, v55
	v_cvt_pk_bf16_f32 v166, v48, v49
	v_cvt_pk_bf16_f32 v167, v50, v51
	v_lshl_add_u64 v[170:171], v[170:171], 0, v[144:145]
	global_store_dwordx4 v[170:171], v[164:167], off
	s_nop 1
	v_cvt_pk_bf16_f32 v164, v28, v29
	v_cvt_pk_bf16_f32 v165, v30, v31
	v_cvt_pk_bf16_f32 v166, v24, v25
	v_cvt_pk_bf16_f32 v167, v26, v27
	global_store_dwordx4 v[170:171], v[164:167], off offset:256
	v_mad_i64_i32 v[170:171], s[28:29], v158, s52, v[168:169]
	v_lshl_add_u64 v[170:171], v[170:171], 0, s[4:5]
	v_cvt_pk_bf16_f32 v164, v36, v37
	v_cvt_pk_bf16_f32 v165, v38, v39
	v_cvt_pk_bf16_f32 v166, v32, v33
	v_cvt_pk_bf16_f32 v167, v34, v35
	v_lshl_add_u64 v[170:171], v[170:171], 0, v[144:145]
	v_mad_i64_i32 v[168:169], s[28:29], v157, s52, v[168:169]
	global_store_dwordx4 v[170:171], v[164:167], off
	v_lshl_add_u64 v[168:169], v[168:169], 0, s[4:5]
	v_lshl_add_u64 v[168:169], v[168:169], 0, v[144:145]
	v_cvt_pk_bf16_f32 v164, v12, v13
	v_cvt_pk_bf16_f32 v165, v14, v15
	v_cvt_pk_bf16_f32 v166, v8, v9
	v_cvt_pk_bf16_f32 v167, v10, v11
	global_store_dwordx4 v[170:171], v[164:167], off offset:256
	s_mov_b64 s[28:29], 0
	s_nop 0
	v_cvt_pk_bf16_f32 v164, v20, v21
	v_cvt_pk_bf16_f32 v165, v22, v23
	v_cvt_pk_bf16_f32 v166, v16, v17
	v_cvt_pk_bf16_f32 v167, v18, v19
	global_store_dwordx4 v[168:169], v[164:167], off
	s_nop 1
	v_cvt_pk_bf16_f32 v164, v4, v5
	v_cvt_pk_bf16_f32 v165, v6, v7
	v_cvt_pk_bf16_f32 v166, v0, v1
	v_cvt_pk_bf16_f32 v167, v2, v3
	global_store_dwordx4 v[168:169], v[164:167], off offset:256

.LBB0_1401:
	s_add_u32 s67, s34, 0x100
	v_mov_b32_e32 v0, 0
	s_addc_u32 s68, s35, 0
	s_mov_b32 s69, -2
	v_mov_b32_e32 v1, v0
	v_mov_b32_e32 v2, v0
	v_mov_b32_e32 v3, v0
	v_mov_b32_e32 v4, v0
	v_mov_b32_e32 v5, v0
	v_mov_b32_e32 v6, v0
	v_mov_b32_e32 v7, v0
	v_mov_b32_e32 v8, v0
	v_mov_b32_e32 v9, v0
	v_mov_b32_e32 v10, v0
	v_mov_b32_e32 v11, v0
	v_mov_b32_e32 v12, v0
	v_mov_b32_e32 v13, v0
	v_mov_b32_e32 v14, v0
	v_mov_b32_e32 v15, v0
	v_mov_b32_e32 v24, v0
	v_mov_b32_e32 v25, v0
	v_mov_b32_e32 v26, v0
	v_mov_b32_e32 v27, v0
	v_mov_b32_e32 v28, v0
	v_mov_b32_e32 v29, v0
	v_mov_b32_e32 v30, v0
	v_mov_b32_e32 v31, v0
	v_mov_b32_e32 v40, v0
	v_mov_b32_e32 v41, v0
	v_mov_b32_e32 v42, v0
	v_mov_b32_e32 v43, v0
	v_mov_b32_e32 v44, v0
	v_mov_b32_e32 v45, v0
	v_mov_b32_e32 v46, v0
	v_mov_b32_e32 v47, v0
	v_mov_b32_e32 v16, v0
	v_mov_b32_e32 v17, v0
	v_mov_b32_e32 v18, v0
	v_mov_b32_e32 v19, v0
	v_mov_b32_e32 v20, v0
	v_mov_b32_e32 v21, v0
	v_mov_b32_e32 v22, v0
	v_mov_b32_e32 v23, v0
	v_mov_b32_e32 v32, v0
	v_mov_b32_e32 v33, v0
	v_mov_b32_e32 v34, v0
	v_mov_b32_e32 v35, v0
	v_mov_b32_e32 v36, v0
	v_mov_b32_e32 v37, v0
	v_mov_b32_e32 v38, v0
	v_mov_b32_e32 v39, v0
	v_mov_b32_e32 v48, v0
	v_mov_b32_e32 v49, v0
	v_mov_b32_e32 v50, v0
	v_mov_b32_e32 v51, v0
	v_mov_b32_e32 v52, v0
	v_mov_b32_e32 v53, v0
	v_mov_b32_e32 v54, v0
	v_mov_b32_e32 v55, v0
	v_mov_b32_e32 v56, v0
	v_mov_b32_e32 v57, v0
	v_mov_b32_e32 v58, v0
	v_mov_b32_e32 v59, v0
	v_mov_b32_e32 v60, v0
	v_mov_b32_e32 v61, v0
	v_mov_b32_e32 v62, v0
	v_mov_b32_e32 v63, v0
	v_mov_b32_e32 v64, v0
	v_mov_b32_e32 v65, v0
	v_mov_b32_e32 v66, v0
	v_mov_b32_e32 v67, v0
	v_mov_b32_e32 v68, v0
	v_mov_b32_e32 v69, v0
	v_mov_b32_e32 v70, v0
	v_mov_b32_e32 v71, v0
	v_mov_b32_e32 v72, v0
	v_mov_b32_e32 v73, v0
	v_mov_b32_e32 v74, v0
	v_mov_b32_e32 v75, v0
	v_mov_b32_e32 v76, v0
	v_mov_b32_e32 v77, v0
	v_mov_b32_e32 v78, v0
	v_mov_b32_e32 v79, v0
	v_mov_b32_e32 v88, v0
	v_mov_b32_e32 v89, v0
	v_mov_b32_e32 v90, v0
	v_mov_b32_e32 v91, v0
	v_mov_b32_e32 v92, v0
	v_mov_b32_e32 v93, v0
	v_mov_b32_e32 v94, v0
	v_mov_b32_e32 v95, v0
	v_mov_b32_e32 v104, v0
	v_mov_b32_e32 v105, v0
	v_mov_b32_e32 v106, v0
	v_mov_b32_e32 v107, v0
	v_mov_b32_e32 v108, v0
	v_mov_b32_e32 v109, v0
	v_mov_b32_e32 v110, v0
	v_mov_b32_e32 v111, v0
	v_mov_b32_e32 v80, v0
	v_mov_b32_e32 v81, v0
	v_mov_b32_e32 v82, v0
	v_mov_b32_e32 v83, v0
	v_mov_b32_e32 v84, v0
	v_mov_b32_e32 v85, v0
	v_mov_b32_e32 v86, v0
	v_mov_b32_e32 v87, v0
	v_mov_b32_e32 v96, v0
	v_mov_b32_e32 v97, v0
	v_mov_b32_e32 v98, v0
	v_mov_b32_e32 v99, v0
	v_mov_b32_e32 v100, v0
	v_mov_b32_e32 v101, v0
	v_mov_b32_e32 v102, v0
	v_mov_b32_e32 v103, v0
	v_mov_b32_e32 v112, v0
	v_mov_b32_e32 v113, v0
	v_mov_b32_e32 v114, v0
	v_mov_b32_e32 v115, v0
	v_mov_b32_e32 v116, v0
	v_mov_b32_e32 v117, v0
	v_mov_b32_e32 v118, v0
	v_mov_b32_e32 v119, v0
	v_mov_b32_e32 v120, v0
	v_mov_b32_e32 v121, v0
	v_mov_b32_e32 v122, v0
	v_mov_b32_e32 v123, v0
	v_mov_b32_e32 v124, v0
	v_mov_b32_e32 v125, v0
	v_mov_b32_e32 v126, v0
	v_mov_b32_e32 v127, v0
	ds_read_b128 v[150:153], v147
	ds_read_b128 v[154:157], v147 offset:1024
	ds_read_b128 v[158:161], v147 offset:2048
	ds_read_b128 v[162:165], v147 offset:3072
.LBB0_1402:
	s_add_u32 s34, s30, 0x100
	s_addc_u32 s35, s31, 0
	s_cmp_eq_u32 s69, 36
	s_cselect_b32 s39, s5, s35
	s_cselect_b32 s38, s4, s34
	s_cselect_b32 s37, s7, s68
	s_cselect_b32 s36, s6, s67
	v_lshl_add_u64 v[198:199], s[30:31], 0, v[136:137]
	s_add_i32 m0, s41, 0xc000
	ds_read_b128 v[166:169], v148
	ds_read_b128 v[170:173], v148 offset:1024
	ds_read_b128 v[174:177], v148 offset:2048
	ds_read_b128 v[178:181], v148 offset:3072
	ds_read_b128 v[182:185], v148 offset:4096
	ds_read_b128 v[186:189], v148 offset:5120
	ds_read_b128 v[190:193], v148 offset:6144
	ds_read_b128 v[194:197], v148 offset:7168
	global_load_lds_dwordx4 v[198:199], off
	v_lshl_add_u64 v[198:199], s[30:31], 0, v[138:139]
	s_add_i32 m0, s41, 0xe000
	s_nop 0
	global_load_lds_dwordx4 v[198:199], off
	s_waitcnt lgkmcnt(8)
	s_barrier
	s_waitcnt lgkmcnt(0)
	s_setprio 1
	s_waitcnt lgkmcnt(0)
	v_mfma_f32_16x16x32_bf16 v[124:127], v[150:153], v[166:169], v[124:127]
	v_mfma_f32_16x16x32_bf16 v[120:123], v[158:161], v[166:169], v[120:123]
	v_mfma_f32_16x16x32_bf16 v[116:119], v[150:153], v[174:177], v[116:119]
	v_mfma_f32_16x16x32_bf16 v[112:115], v[158:161], v[174:177], v[112:115]
	v_mfma_f32_16x16x32_bf16 v[100:103], v[150:153], v[182:185], v[100:103]
	v_mfma_f32_16x16x32_bf16 v[96:99], v[158:161], v[182:185], v[96:99]
	v_mfma_f32_16x16x32_bf16 v[84:87], v[150:153], v[190:193], v[84:87]
	v_mfma_f32_16x16x32_bf16 v[80:83], v[158:161], v[190:193], v[80:83]
	v_mfma_f32_16x16x32_bf16 v[124:127], v[154:157], v[170:173], v[124:127]
	v_mfma_f32_16x16x32_bf16 v[120:123], v[162:165], v[170:173], v[120:123]
	v_mfma_f32_16x16x32_bf16 v[116:119], v[154:157], v[178:181], v[116:119]
	v_mfma_f32_16x16x32_bf16 v[112:115], v[162:165], v[178:181], v[112:115]
	v_mfma_f32_16x16x32_bf16 v[100:103], v[154:157], v[186:189], v[100:103]
	v_mfma_f32_16x16x32_bf16 v[96:99], v[162:165], v[186:189], v[96:99]
	v_mfma_f32_16x16x32_bf16 v[84:87], v[154:157], v[194:197], v[84:87]
	v_mfma_f32_16x16x32_bf16 v[80:83], v[162:165], v[194:197], v[80:83]
	s_setprio 0
	s_barrier
	s_add_i32 s30, s54, s40
	v_lshl_add_u64 v[206:207], s[36:37], 0, v[130:131]
	s_mov_b32 m0, s30
	ds_read_b128 v[198:201], v149
	ds_read_b128 v[202:205], v149 offset:1024
	ds_read_b128 v[210:213], v149 offset:2048
	ds_read_b128 v[214:217], v149 offset:3072
	global_load_lds_dwordx4 v[206:207], off
	v_lshl_add_u64 v[218:219], s[36:37], 0, v[134:135]
	s_add_i32 m0, s30, 0x2000
	s_nop 0
	global_load_lds_dwordx4 v[218:219], off
	s_barrier
	s_waitcnt lgkmcnt(0)
	s_setprio 1
	s_waitcnt lgkmcnt(0)
	v_mfma_f32_16x16x32_bf16 v[108:111], v[198:201], v[166:169], v[108:111]
	v_mfma_f32_16x16x32_bf16 v[104:107], v[210:213], v[166:169], v[104:107]
	v_mfma_f32_16x16x32_bf16 v[92:95], v[198:201], v[174:177], v[92:95]
	v_mfma_f32_16x16x32_bf16 v[88:91], v[210:213], v[174:177], v[88:91]
	v_mfma_f32_16x16x32_bf16 v[76:79], v[198:201], v[182:185], v[76:79]
	v_mfma_f32_16x16x32_bf16 v[72:75], v[210:213], v[182:185], v[72:75]
	v_mfma_f32_16x16x32_bf16 v[68:71], v[198:201], v[190:193], v[68:71]
	v_mfma_f32_16x16x32_bf16 v[64:67], v[210:213], v[190:193], v[64:67]
	v_mfma_f32_16x16x32_bf16 v[108:111], v[202:205], v[170:173], v[108:111]
	v_mfma_f32_16x16x32_bf16 v[104:107], v[214:217], v[170:173], v[104:107]
	v_mfma_f32_16x16x32_bf16 v[92:95], v[202:205], v[178:181], v[92:95]
	v_mfma_f32_16x16x32_bf16 v[88:91], v[214:217], v[178:181], v[88:91]
	v_mfma_f32_16x16x32_bf16 v[76:79], v[202:205], v[186:189], v[76:79]
	v_mfma_f32_16x16x32_bf16 v[72:75], v[214:217], v[186:189], v[72:75]
	v_mfma_f32_16x16x32_bf16 v[68:71], v[202:205], v[194:197], v[68:71]
	v_mfma_f32_16x16x32_bf16 v[64:67], v[214:217], v[194:197], v[64:67]
	s_setprio 0
	s_mov_b32 m0, s41
	v_lshl_add_u64 v[220:221], s[38:39], 0, v[128:129]
	s_barrier
	ds_read_b128 v[166:169], v148 offset:16384
	ds_read_b128 v[170:173], v148 offset:17408
	ds_read_b128 v[174:177], v148 offset:18432
	ds_read_b128 v[178:181], v148 offset:19456
	ds_read_b128 v[182:185], v148 offset:20480
	ds_read_b128 v[186:189], v148 offset:21504
	ds_read_b128 v[190:193], v148 offset:22528
	ds_read_b128 v[194:197], v148 offset:23552
	global_load_lds_dwordx4 v[220:221], off
	v_lshl_add_u64 v[222:223], s[38:39], 0, v[132:133]
	s_mov_b32 m0, s42
	s_nop 0
	global_load_lds_dwordx4 v[222:223], off
	s_waitcnt vmcnt(10)
	s_barrier
	s_waitcnt lgkmcnt(0)
	s_setprio 1
	s_waitcnt lgkmcnt(0)
	v_mfma_f32_16x16x32_bf16 v[60:63], v[150:153], v[166:169], v[60:63]
	v_mfma_f32_16x16x32_bf16 v[56:59], v[158:161], v[166:169], v[56:59]
	v_mfma_f32_16x16x32_bf16 v[52:55], v[150:153], v[174:177], v[52:55]
	v_mfma_f32_16x16x32_bf16 v[48:51], v[158:161], v[174:177], v[48:51]
	v_mfma_f32_16x16x32_bf16 v[36:39], v[150:153], v[182:185], v[36:39]
	v_mfma_f32_16x16x32_bf16 v[32:35], v[158:161], v[182:185], v[32:35]
	v_mfma_f32_16x16x32_bf16 v[20:23], v[150:153], v[190:193], v[20:23]
	v_mfma_f32_16x16x32_bf16 v[16:19], v[158:161], v[190:193], v[16:19]
	v_mfma_f32_16x16x32_bf16 v[60:63], v[154:157], v[170:173], v[60:63]
	v_mfma_f32_16x16x32_bf16 v[56:59], v[162:165], v[170:173], v[56:59]
	v_mfma_f32_16x16x32_bf16 v[52:55], v[154:157], v[178:181], v[52:55]
	v_mfma_f32_16x16x32_bf16 v[48:51], v[162:165], v[178:181], v[48:51]
	v_mfma_f32_16x16x32_bf16 v[36:39], v[154:157], v[186:189], v[36:39]
	v_mfma_f32_16x16x32_bf16 v[32:35], v[162:165], v[186:189], v[32:35]
	v_mfma_f32_16x16x32_bf16 v[20:23], v[154:157], v[194:197], v[20:23]
	v_mfma_f32_16x16x32_bf16 v[16:19], v[162:165], v[194:197], v[16:19]
	s_setprio 0
	s_barrier
	s_add_u32 s30, s36, 0xa0000
	s_addc_u32 s31, s37, 0
	s_add_i32 s70, s55, s40
	v_lshl_add_u64 v[150:151], s[30:31], 0, v[130:131]
	s_mov_b32 m0, s70
	s_nop 0
	global_load_lds_dwordx4 v[150:151], off
	v_lshl_add_u64 v[150:151], s[30:31], 0, v[134:135]
	s_add_i32 m0, s70, 0x2000
	s_nop 0
	global_load_lds_dwordx4 v[150:151], off
	s_add_i32 s70, 0, 0x18000
	v_add_u32_e32 v162, s70, v146
	ds_read_b128 v[150:153], v162
	ds_read_b128 v[154:157], v162 offset:1024
	ds_read_b128 v[158:161], v162 offset:2048
	ds_read_b128 v[162:165], v162 offset:3072
	s_waitcnt vmcnt(6)
	s_barrier
	s_setprio 1
	v_mfma_f32_16x16x32_bf16 v[44:47], v[198:201], v[166:169], v[44:47]
	v_mfma_f32_16x16x32_bf16 v[40:43], v[210:213], v[166:169], v[40:43]
	v_mfma_f32_16x16x32_bf16 v[28:31], v[198:201], v[174:177], v[28:31]
	v_mfma_f32_16x16x32_bf16 v[24:27], v[210:213], v[174:177], v[24:27]
	v_mfma_f32_16x16x32_bf16 v[12:15], v[198:201], v[182:185], v[12:15]
	v_mfma_f32_16x16x32_bf16 v[8:11], v[210:213], v[182:185], v[8:11]
	v_mfma_f32_16x16x32_bf16 v[4:7], v[198:201], v[190:193], v[4:7]
	v_mfma_f32_16x16x32_bf16 v[0:3], v[210:213], v[190:193], v[0:3]
	v_mfma_f32_16x16x32_bf16 v[44:47], v[202:205], v[170:173], v[44:47]
	v_mfma_f32_16x16x32_bf16 v[40:43], v[214:217], v[170:173], v[40:43]
	v_mfma_f32_16x16x32_bf16 v[28:31], v[202:205], v[178:181], v[28:31]
	v_mfma_f32_16x16x32_bf16 v[24:27], v[214:217], v[178:181], v[24:27]
	v_mfma_f32_16x16x32_bf16 v[12:15], v[202:205], v[186:189], v[12:15]
	v_mfma_f32_16x16x32_bf16 v[8:11], v[214:217], v[186:189], v[8:11]
	v_mfma_f32_16x16x32_bf16 v[4:7], v[202:205], v[194:197], v[4:7]
	v_mfma_f32_16x16x32_bf16 v[0:3], v[214:217], v[194:197], v[0:3]
	s_setprio 0
	s_barrier
	s_add_u32 s30, s38, 0xa0000
	s_addc_u32 s31, s39, 0
	s_mov_b32 m0, s43
	v_lshl_add_u64 v[198:199], s[30:31], 0, v[128:129]
	ds_read_b128 v[166:169], v148 offset:32768
	ds_read_b128 v[170:173], v148 offset:33792
	ds_read_b128 v[174:177], v148 offset:34816
	ds_read_b128 v[178:181], v148 offset:35840
	ds_read_b128 v[182:185], v148 offset:36864
	ds_read_b128 v[186:189], v148 offset:37888
	ds_read_b128 v[190:193], v148 offset:38912
	ds_read_b128 v[194:197], v148 offset:39936
	global_load_lds_dwordx4 v[198:199], off
	v_lshl_add_u64 v[198:199], s[30:31], 0, v[132:133]
	s_mov_b32 m0, s44
	s_nop 0
	global_load_lds_dwordx4 v[198:199], off
	s_waitcnt lgkmcnt(8)
	s_barrier
	s_waitcnt lgkmcnt(0)
	s_setprio 1
	s_waitcnt lgkmcnt(0)
	v_mfma_f32_16x16x32_bf16 v[124:127], v[150:153], v[166:169], v[124:127]
	v_mfma_f32_16x16x32_bf16 v[120:123], v[158:161], v[166:169], v[120:123]
	v_mfma_f32_16x16x32_bf16 v[116:119], v[150:153], v[174:177], v[116:119]
	v_mfma_f32_16x16x32_bf16 v[112:115], v[158:161], v[174:177], v[112:115]
	v_mfma_f32_16x16x32_bf16 v[100:103], v[150:153], v[182:185], v[100:103]
	v_mfma_f32_16x16x32_bf16 v[96:99], v[158:161], v[182:185], v[96:99]
	v_mfma_f32_16x16x32_bf16 v[84:87], v[150:153], v[190:193], v[84:87]
	v_mfma_f32_16x16x32_bf16 v[80:83], v[158:161], v[190:193], v[80:83]
	v_mfma_f32_16x16x32_bf16 v[124:127], v[154:157], v[170:173], v[124:127]
	v_mfma_f32_16x16x32_bf16 v[120:123], v[162:165], v[170:173], v[120:123]
	v_mfma_f32_16x16x32_bf16 v[116:119], v[154:157], v[178:181], v[116:119]
	v_mfma_f32_16x16x32_bf16 v[112:115], v[162:165], v[178:181], v[112:115]
	v_mfma_f32_16x16x32_bf16 v[100:103], v[154:157], v[186:189], v[100:103]
	v_mfma_f32_16x16x32_bf16 v[96:99], v[162:165], v[186:189], v[96:99]
	v_mfma_f32_16x16x32_bf16 v[84:87], v[154:157], v[194:197], v[84:87]
	v_mfma_f32_16x16x32_bf16 v[80:83], v[162:165], v[194:197], v[80:83]
	s_setprio 0
	s_barrier
	s_add_i32 s38, 0, 0x1c000
	s_add_i32 s30, s70, s40
	v_add_u32_e32 v214, s38, v146
	v_lshl_add_u64 v[206:207], v[206:207], 0, s[14:15]
	s_mov_b32 m0, s30
	ds_read_b128 v[198:201], v214
	ds_read_b128 v[202:205], v214 offset:1024
	ds_read_b128 v[210:213], v214 offset:2048
	ds_read_b128 v[214:217], v214 offset:3072
	global_load_lds_dwordx4 v[206:207], off
	v_lshl_add_u64 v[206:207], v[218:219], 0, s[14:15]
	s_add_i32 m0, s30, 0x2000
	s_nop 0
	global_load_lds_dwordx4 v[206:207], off
	s_barrier
	s_waitcnt lgkmcnt(0)
	s_setprio 1
	s_waitcnt lgkmcnt(0)
	v_mfma_f32_16x16x32_bf16 v[108:111], v[198:201], v[166:169], v[108:111]
	v_mfma_f32_16x16x32_bf16 v[104:107], v[210:213], v[166:169], v[104:107]
	v_mfma_f32_16x16x32_bf16 v[92:95], v[198:201], v[174:177], v[92:95]
	v_mfma_f32_16x16x32_bf16 v[88:91], v[210:213], v[174:177], v[88:91]
	v_mfma_f32_16x16x32_bf16 v[76:79], v[198:201], v[182:185], v[76:79]
	v_mfma_f32_16x16x32_bf16 v[72:75], v[210:213], v[182:185], v[72:75]
	v_mfma_f32_16x16x32_bf16 v[68:71], v[198:201], v[190:193], v[68:71]
	v_mfma_f32_16x16x32_bf16 v[64:67], v[210:213], v[190:193], v[64:67]
	v_mfma_f32_16x16x32_bf16 v[108:111], v[202:205], v[170:173], v[108:111]
	v_mfma_f32_16x16x32_bf16 v[104:107], v[214:217], v[170:173], v[104:107]
	v_mfma_f32_16x16x32_bf16 v[92:95], v[202:205], v[178:181], v[92:95]
	v_mfma_f32_16x16x32_bf16 v[88:91], v[214:217], v[178:181], v[88:91]
	v_mfma_f32_16x16x32_bf16 v[76:79], v[202:205], v[186:189], v[76:79]
	v_mfma_f32_16x16x32_bf16 v[72:75], v[214:217], v[186:189], v[72:75]
	v_mfma_f32_16x16x32_bf16 v[68:71], v[202:205], v[194:197], v[68:71]
	v_mfma_f32_16x16x32_bf16 v[64:67], v[214:217], v[194:197], v[64:67]
	s_setprio 0
	s_mov_b32 m0, s52
	v_lshl_add_u64 v[206:207], v[220:221], 0, s[14:15]
	s_barrier
	ds_read_b128 v[166:169], v148 offset:49152
	ds_read_b128 v[170:173], v148 offset:50176
	ds_read_b128 v[174:177], v148 offset:51200
	ds_read_b128 v[178:181], v148 offset:52224
	ds_read_b128 v[182:185], v148 offset:53248
	ds_read_b128 v[186:189], v148 offset:54272
	ds_read_b128 v[190:193], v148 offset:55296
	ds_read_b128 v[194:197], v148 offset:56320
	global_load_lds_dwordx4 v[206:207], off
	v_lshl_add_u64 v[206:207], v[222:223], 0, s[14:15]
	s_mov_b32 m0, s53
	s_nop 0
	global_load_lds_dwordx4 v[206:207], off
	s_waitcnt vmcnt(10)
	s_barrier
	s_waitcnt lgkmcnt(0)
	s_setprio 1
	s_waitcnt lgkmcnt(0)
	v_mfma_f32_16x16x32_bf16 v[60:63], v[150:153], v[166:169], v[60:63]
	v_mfma_f32_16x16x32_bf16 v[56:59], v[158:161], v[166:169], v[56:59]
	v_mfma_f32_16x16x32_bf16 v[52:55], v[150:153], v[174:177], v[52:55]
	v_mfma_f32_16x16x32_bf16 v[48:51], v[158:161], v[174:177], v[48:51]
	v_mfma_f32_16x16x32_bf16 v[36:39], v[150:153], v[182:185], v[36:39]
	v_mfma_f32_16x16x32_bf16 v[32:35], v[158:161], v[182:185], v[32:35]
	v_mfma_f32_16x16x32_bf16 v[20:23], v[150:153], v[190:193], v[20:23]
	v_mfma_f32_16x16x32_bf16 v[16:19], v[158:161], v[190:193], v[16:19]
	v_mfma_f32_16x16x32_bf16 v[60:63], v[154:157], v[170:173], v[60:63]
	v_mfma_f32_16x16x32_bf16 v[56:59], v[162:165], v[170:173], v[56:59]
	v_mfma_f32_16x16x32_bf16 v[52:55], v[154:157], v[178:181], v[52:55]
	v_mfma_f32_16x16x32_bf16 v[48:51], v[162:165], v[178:181], v[48:51]
	v_mfma_f32_16x16x32_bf16 v[36:39], v[154:157], v[186:189], v[36:39]
	v_mfma_f32_16x16x32_bf16 v[32:35], v[162:165], v[186:189], v[32:35]
	v_mfma_f32_16x16x32_bf16 v[20:23], v[154:157], v[194:197], v[20:23]
	v_mfma_f32_16x16x32_bf16 v[16:19], v[162:165], v[194:197], v[16:19]
	s_setprio 0
	s_barrier
	s_add_u32 s30, s36, 0xa0080
	s_addc_u32 s31, s37, 0
	s_add_i32 s36, s38, s40
	v_lshl_add_u64 v[150:151], s[30:31], 0, v[130:131]
	s_mov_b32 m0, s36
	s_nop 0
	global_load_lds_dwordx4 v[150:151], off
	v_lshl_add_u64 v[150:151], s[30:31], 0, v[134:135]
	s_add_i32 m0, s36, 0x2000
	s_nop 0
	global_load_lds_dwordx4 v[150:151], off
	ds_read_b128 v[150:153], v147
	ds_read_b128 v[154:157], v147 offset:1024
	ds_read_b128 v[158:161], v147 offset:2048
	ds_read_b128 v[162:165], v147 offset:3072
	s_waitcnt vmcnt(6)
	s_barrier
	s_setprio 1
	s_waitcnt lgkmcnt(0)
	v_mfma_f32_16x16x32_bf16 v[44:47], v[198:201], v[166:169], v[44:47]
	v_mfma_f32_16x16x32_bf16 v[40:43], v[210:213], v[166:169], v[40:43]
	v_mfma_f32_16x16x32_bf16 v[28:31], v[198:201], v[174:177], v[28:31]
	v_mfma_f32_16x16x32_bf16 v[24:27], v[210:213], v[174:177], v[24:27]
	v_mfma_f32_16x16x32_bf16 v[12:15], v[198:201], v[182:185], v[12:15]
	v_mfma_f32_16x16x32_bf16 v[8:11], v[210:213], v[182:185], v[8:11]
	v_mfma_f32_16x16x32_bf16 v[4:7], v[198:201], v[190:193], v[4:7]
	v_mfma_f32_16x16x32_bf16 v[0:3], v[210:213], v[190:193], v[0:3]
	v_mfma_f32_16x16x32_bf16 v[44:47], v[202:205], v[170:173], v[44:47]
	v_mfma_f32_16x16x32_bf16 v[40:43], v[214:217], v[170:173], v[40:43]
	v_mfma_f32_16x16x32_bf16 v[28:31], v[202:205], v[178:181], v[28:31]
	v_mfma_f32_16x16x32_bf16 v[24:27], v[214:217], v[178:181], v[24:27]
	v_mfma_f32_16x16x32_bf16 v[12:15], v[202:205], v[186:189], v[12:15]
	v_mfma_f32_16x16x32_bf16 v[8:11], v[214:217], v[186:189], v[8:11]
	v_mfma_f32_16x16x32_bf16 v[4:7], v[202:205], v[194:197], v[4:7]
	v_mfma_f32_16x16x32_bf16 v[0:3], v[214:217], v[194:197], v[0:3]
	s_setprio 0
	s_add_i32 s69, s69, 2
	s_add_u32 s67, s67, 0x100
	s_addc_u32 s68, s68, 0
	s_cmp_gt_u32 s69, 37
	s_mov_b64 s[30:31], s[34:35]
	s_barrier
	s_cbranch_scc0 .LBB0_1402
	v_mov_b32_e32 v150, v145
	v_mov_b32_e32 v151, v144
	s_lshl_b32 s30, s63, 8
	s_add_i32 s30, s30, s49
	v_add_u32_e32 v150, s30, v150
	s_lshl_b32 s30, s66, 8
	s_or_b32 s30, s30, s51
	v_lshl_add_u32 v152, v151, 3, s30
	v_ashrrev_i32_e32 v151, 31, v150
	v_lshlrev_b64 v[150:151], 12, v[150:151]
	v_ashrrev_i32_e32 v153, 31, v152
	v_lshl_add_u64 v[150:151], s[10:11], 0, v[150:151]
	v_lshl_add_u64 v[150:151], v[152:153], 1, v[150:151]
	v_cvt_pk_bf16_f32 v108, v108, v109
	v_cvt_pk_bf16_f32 v109, v110, v111
	v_cvt_pk_bf16_f32 v110, v104, v105
	v_cvt_pk_bf16_f32 v111, v106, v107
	global_store_dwordx4 v[150:151], v[108:111], off offset:256
	v_cvt_pk_bf16_f32 v92, v92, v93
	v_cvt_pk_bf16_f32 v93, v94, v95
	v_add_co_u32_e32 v110, vcc, s48, v150
	v_lshl_add_u64 v[108:109], v[150:151], 0, s[18:19]
	s_nop 0
	v_addc_co_u32_e32 v111, vcc, 0, v151, vcc
	v_cvt_pk_bf16_f32 v94, v88, v89
	v_cvt_pk_bf16_f32 v95, v90, v91
	global_store_dwordx4 v[108:109], v[92:95], off offset:256
	v_cvt_pk_bf16_f32 v76, v76, v77
	v_cvt_pk_bf16_f32 v77, v78, v79
	v_add_co_u32_e32 v94, vcc, s56, v150
	v_lshl_add_u64 v[92:93], v[150:151], 0, s[20:21]
	s_nop 0
	v_addc_co_u32_e32 v95, vcc, 0, v151, vcc
	v_cvt_pk_bf16_f32 v78, v72, v73
	v_cvt_pk_bf16_f32 v79, v74, v75
	global_store_dwordx4 v[92:93], v[76:79], off offset:256
	v_cvt_pk_bf16_f32 v60, v60, v61
	v_cvt_pk_bf16_f32 v61, v62, v63
	v_add_co_u32_e32 v78, vcc, s57, v150
	v_cvt_pk_bf16_f32 v62, v56, v57
	s_nop 0
	v_addc_co_u32_e32 v79, vcc, 0, v151, vcc
	v_add_co_u32_e32 v56, vcc, s59, v150
	v_cvt_pk_bf16_f32 v68, v68, v69
	v_cvt_pk_bf16_f32 v69, v70, v71
	v_cvt_pk_bf16_f32 v70, v64, v65
	v_lshl_add_u64 v[64:65], v[150:151], 0, s[24:25]
	v_addc_co_u32_e32 v57, vcc, 0, v151, vcc
	v_cvt_pk_bf16_f32 v44, v44, v45
	v_cvt_pk_bf16_f32 v45, v46, v47
	v_cvt_pk_bf16_f32 v46, v40, v41
	v_cvt_pk_bf16_f32 v47, v42, v43
	global_store_dwordx4 v[64:65], v[44:47], off offset:256
	v_cvt_pk_bf16_f32 v28, v28, v29
	v_cvt_pk_bf16_f32 v29, v30, v31
	v_add_co_u32_e32 v46, vcc, s60, v150
	v_lshl_add_u64 v[44:45], v[150:151], 0, s[26:27]
	s_nop 0
	v_addc_co_u32_e32 v47, vcc, 0, v151, vcc
	v_cvt_pk_bf16_f32 v30, v24, v25
	v_cvt_pk_bf16_f32 v31, v26, v27
	global_store_dwordx4 v[44:45], v[28:31], off offset:256
	v_cvt_pk_bf16_f32 v12, v12, v13
	v_cvt_pk_bf16_f32 v13, v14, v15
	v_add_co_u32_e32 v30, vcc, s61, v150
	v_lshl_add_u64 v[28:29], v[150:151], 0, s[8:9]
	s_nop 0
	v_addc_co_u32_e32 v31, vcc, 0, v151, vcc
	v_cvt_pk_bf16_f32 v14, v8, v9
	v_cvt_pk_bf16_f32 v15, v10, v11
	global_store_dwordx4 v[28:29], v[12:15], off offset:256
	v_cvt_pk_bf16_f32 v124, v124, v125
	v_cvt_pk_bf16_f32 v125, v126, v127
	v_add_co_u32_e32 v14, vcc, s62, v150
	v_cvt_pk_bf16_f32 v126, v120, v121
	s_nop 0
	v_addc_co_u32_e32 v15, vcc, 0, v151, vcc
	v_cvt_pk_bf16_f32 v127, v122, v123
	v_cvt_pk_bf16_f32 v104, v116, v117
	v_cvt_pk_bf16_f32 v105, v118, v119
	v_cvt_pk_bf16_f32 v106, v112, v113
	v_cvt_pk_bf16_f32 v107, v114, v115
	v_cvt_pk_bf16_f32 v88, v100, v101
	v_cvt_pk_bf16_f32 v89, v102, v103
	v_cvt_pk_bf16_f32 v90, v96, v97
	v_cvt_pk_bf16_f32 v91, v98, v99
	v_lshl_add_u64 v[76:77], v[150:151], 0, s[22:23]
	v_cvt_pk_bf16_f32 v72, v84, v85
	v_cvt_pk_bf16_f32 v73, v86, v87
	v_cvt_pk_bf16_f32 v74, v80, v81
	v_cvt_pk_bf16_f32 v75, v82, v83
	v_cvt_pk_bf16_f32 v71, v66, v67
	v_cvt_pk_bf16_f32 v63, v58, v59
	v_cvt_pk_bf16_f32 v40, v52, v53
	v_cvt_pk_bf16_f32 v41, v54, v55
	v_cvt_pk_bf16_f32 v42, v48, v49
	v_cvt_pk_bf16_f32 v43, v50, v51
	v_cvt_pk_bf16_f32 v24, v36, v37
	v_cvt_pk_bf16_f32 v25, v38, v39
	v_cvt_pk_bf16_f32 v26, v32, v33
	v_cvt_pk_bf16_f32 v27, v34, v35
	v_lshl_add_u64 v[12:13], v[150:151], 0, s[28:29]
	v_cvt_pk_bf16_f32 v8, v20, v21
	v_cvt_pk_bf16_f32 v9, v22, v23
	v_cvt_pk_bf16_f32 v10, v16, v17
	v_cvt_pk_bf16_f32 v11, v18, v19
	v_cvt_pk_bf16_f32 v4, v4, v5
	v_cvt_pk_bf16_f32 v5, v6, v7
	v_cvt_pk_bf16_f32 v6, v0, v1
	v_cvt_pk_bf16_f32 v7, v2, v3
	s_and_b64 vcc, exec, s[2:3]
	s_mov_b32 s66, s64
	s_mov_b32 s63, s65
	s_mov_b64 s[34:35], s[6:7]
	s_mov_b64 s[30:31], s[4:5]
	global_store_dwordx4 v[150:151], v[124:127], off
	global_store_dwordx4 v[110:111], v[104:107], off
	global_store_dwordx4 v[94:95], v[88:91], off
	global_store_dwordx4 v[78:79], v[72:75], off
	global_store_dwordx4 v[76:77], v[68:71], off offset:256
	global_store_dwordx4 v[56:57], v[60:63], off
	global_store_dwordx4 v[46:47], v[40:43], off
	global_store_dwordx4 v[30:31], v[24:27], off
	global_store_dwordx4 v[14:15], v[8:11], off
	global_store_dwordx4 v[12:13], v[4:7], off offset:256
	s_cbranch_vccz .LBB0_1391
	s_waitcnt vmcnt(0)
	s_cmpk_gt_u32 s33, 0xff
	s_cbranch_scc1 .LBB0_1406
	s_barrier
